# epilogues de-serialized: SwiGLU row-stat loads hoisted with counted waits; residual-update x reads software-pipelined (3 row groups in flight), stores not drained; fast-loop DMA via scalar base
# speedup vs baseline: 1.0175x; 1.0175x over previous
; __device__ __forceinline__ u32x4 pack8(const f32x4 a, const f32x4 b) { u32x4 w; w.x = cvt_pk_bf16(a[0], a[1]); w.y = cvt_pk_bf16(a[2], a[3]); w.z = cvt_pk_bf16(b[0], b[1]); w.w = cvt_pk_bf16(b[2], b[3]); return w; }
; __device__ __forceinline__ float rstd_of(const float* ssq, int row) { const f32x4 a = *(const f32x4*)(ssq + (size_t)row * 4);
;     return __builtin_amdgcn_rsqf(((a[0] + a[1]) + (a[2] + a[3])) * (1.0f / 1024.0f) + 1e-6f); }
; __device__ __forceinline__ float sigm(float g) { return __builtin_amdgcn_rcpf(1.0f + __builtin_amdgcn_exp2f(-1.4426950408889634f * g)); }
;     __device__ __forceinline__ void operator()(const f32x4 (&acc)[2][2][4][2], const Unit& u, int wr, int wc, int fr, int fq) const {
;         const int row0 = u.pm * BM + wr * 64 + fr, col0 = u.pn * 128 + wc * 32 + 8 * fq;
; #pragma unroll
;         for (int ai = 0; ai < 2; ++ai)
; #pragma unroll
;             for (int m = 0; m < 4; ++m) { if (m == 0) asm volatile("" ::: "memory"); const int row = row0 + ai * HALF + m * 16; const float rs = rstd_of(ssq, row);
;                 f32x4 o[2];
; #pragma unroll
;                 for (int n = 0; n < 2; ++n) { const f32x4 g = acc[ai][0][m][n] * rs, up = acc[ai][1][m][n] * rs;
; #pragma unroll
;                     for (int e = 0; e < 4; ++e) o[n][e] = g[e] * sigm(g[e]) * up[e]; }
;                 *(u32x4*)(O + (size_t)row * 2816 + col0) = pack8(o[0], o[1]); }
.LBB0_121:
	v_lshl_add_u32 v136, s0, 8, v140
	v_ashrrev_i32_e32 v137, 31, v136
	v_lshl_add_u64 v[144:145], v[136:137], 4, s[18:19]
	global_load_dwordx4 v[150:153], v[144:145], off
	global_load_dwordx4 v[154:157], v[144:145], off offset:256
	global_load_dwordx4 v[158:161], v[144:145], off offset:512
	global_load_dwordx4 v[162:165], v[144:145], off offset:768
	global_load_dwordx4 v[166:169], v[144:145], off offset:2048
	global_load_dwordx4 v[170:173], v[144:145], off offset:2304
	global_load_dwordx4 v[174:177], v[144:145], off offset:2560
	global_load_dwordx4 v[178:181], v[144:145], off offset:2816
	v_lshl_or_b32 v138, s1, 7, v142
	v_ashrrev_i32_e32 v139, 31, v138
	s_andn2_b64 vcc, exec, s[6:7]
	s_waitcnt vmcnt(7)
	v_mov_b64_e32 v[144:145], v[150:151]
	v_mov_b64_e32 v[146:147], v[152:153]
	v_mov_b32_e32 v148, v145
	v_mov_b32_e32 v149, v146
	v_mov_b32_e32 v145, v147
	v_pk_add_f32 v[144:145], v[148:149], v[144:145]
	s_nop 0
	v_add_f32_e32 v137, v144, v145
	v_fmamk_f32 v137, v137, 0x3a800000, v231
	v_rsq_f32_e32 v144, v137
	s_nop 0
	v_pk_mul_f32 v[126:127], v[126:127], v[144:145] op_sel_hi:[1,0]
	s_nop 0
	v_mul_f32_e32 v137, 0xbfb8aa3b, v126
	v_exp_f32_e32 v137, v137
	v_pk_mul_f32 v[118:119], v[118:119], v[144:145] op_sel_hi:[1,0]
	v_pk_mul_f32 v[120:121], v[120:121], v[144:145] op_sel_hi:[1,0]
	v_pk_mul_f32 v[122:123], v[122:123], v[144:145] op_sel_hi:[1,0]
	v_add_f32_e32 v137, 1.0, v137
	v_rcp_f32_e32 v146, v137
	v_mul_f32_e32 v137, 0xbfb8aa3b, v127
	v_exp_f32_e32 v137, v137
	v_pk_mul_f32 v[114:115], v[114:115], v[144:145] op_sel_hi:[1,0]
	v_pk_mul_f32 v[116:117], v[116:117], v[144:145] op_sel_hi:[1,0]
	v_add_f32_e32 v137, 1.0, v137
	v_rcp_f32_e32 v147, v137
	s_nop 0
	v_pk_mul_f32 v[126:127], v[126:127], v[146:147]
	s_nop 0
	v_pk_mul_f32 v[118:119], v[118:119], v[126:127]
	v_pk_mul_f32 v[126:127], v[128:129], v[144:145] op_sel_hi:[1,0]
	s_nop 0
	v_mul_f32_e32 v128, 0xbfb8aa3b, v126
	v_mul_f32_e32 v129, 0xbfb8aa3b, v127
	v_exp_f32_e32 v128, v128
	v_exp_f32_e32 v129, v129
	v_add_f32_e32 v128, 1.0, v128
	v_add_f32_e32 v129, 1.0, v129
	v_rcp_f32_e32 v128, v128
	v_rcp_f32_e32 v129, v129
	s_nop 0
	v_pk_mul_f32 v[126:127], v[126:127], v[128:129]
	s_nop 0
	v_pk_mul_f32 v[120:121], v[120:121], v[126:127]
	v_mul_f32_e32 v126, 0xbfb8aa3b, v122
	v_mul_f32_e32 v127, 0xbfb8aa3b, v123
	v_exp_f32_e32 v126, v126
	v_exp_f32_e32 v127, v127
	v_add_f32_e32 v126, 1.0, v126
	v_add_f32_e32 v127, 1.0, v127
	v_rcp_f32_e32 v126, v126
	v_rcp_f32_e32 v127, v127
	s_nop 0
	v_pk_mul_f32 v[122:123], v[122:123], v[126:127]
	s_nop 0
	v_pk_mul_f32 v[122:123], v[114:115], v[122:123]
	v_pk_mul_f32 v[114:115], v[124:125], v[144:145] op_sel_hi:[1,0]
	s_nop 0
	v_mul_f32_e32 v124, 0xbfb8aa3b, v114
	v_mul_f32_e32 v125, 0xbfb8aa3b, v115
	v_exp_f32_e32 v124, v124
	v_exp_f32_e32 v125, v125
	v_add_f32_e32 v124, 1.0, v124
	v_add_f32_e32 v125, 1.0, v125
	v_rcp_f32_e32 v124, v124
	v_rcp_f32_e32 v125, v125
	s_nop 0
	v_pk_mul_f32 v[114:115], v[114:115], v[124:125]
	s_nop 0
	v_pk_mul_f32 v[124:125], v[116:117], v[114:115]
	v_cvt_pk_bf16_f32 v114, v118, v119
	v_mov_b64_e32 v[118:119], s[16:17]
	v_cvt_pk_bf16_f32 v115, v120, v121
	v_cvt_pk_bf16_f32 v116, v122, v123
	v_mad_i64_i32 v[122:123], s[0:1], v136, s92, v[118:119]
	v_lshlrev_b64 v[120:121], 1, v[138:139]
	v_cvt_pk_bf16_f32 v117, v124, v125
	v_lshl_add_u64 v[122:123], v[122:123], 0, v[120:121]
	global_store_dwordx4 v[122:123], v[114:117], off
	s_nop 1
	v_or_b32_e32 v114, 16, v136
	v_ashrrev_i32_e32 v115, 31, v114
	v_lshl_add_u64 v[116:117], v[114:115], 4, s[18:19]
	s_waitcnt vmcnt(7)
	v_mov_b64_e32 v[122:123], v[154:155]
	v_mov_b64_e32 v[124:125], v[156:157]
	v_mov_b32_e32 v116, v123
	v_mov_b32_e32 v117, v124
	v_mov_b32_e32 v123, v125
	v_pk_add_f32 v[116:117], v[116:117], v[122:123]
	s_nop 0
	v_add_f32_e32 v115, v116, v117
	v_fmamk_f32 v115, v115, 0x3a800000, v231
	v_rsq_f32_e32 v116, v115
	s_nop 0
	v_pk_mul_f32 v[108:109], v[108:109], v[116:117] op_sel_hi:[1,0]
	s_nop 0
	v_mul_f32_e32 v115, 0xbfb8aa3b, v108
	v_exp_f32_e32 v115, v115
	v_pk_mul_f32 v[100:101], v[100:101], v[116:117] op_sel_hi:[1,0]
	v_pk_mul_f32 v[102:103], v[102:103], v[116:117] op_sel_hi:[1,0]
	v_pk_mul_f32 v[104:105], v[104:105], v[116:117] op_sel_hi:[1,0]
	v_add_f32_e32 v115, 1.0, v115
	v_rcp_f32_e32 v122, v115
	v_mul_f32_e32 v115, 0xbfb8aa3b, v109
	v_exp_f32_e32 v115, v115
	v_pk_mul_f32 v[96:97], v[96:97], v[116:117] op_sel_hi:[1,0]
	v_pk_mul_f32 v[98:99], v[98:99], v[116:117] op_sel_hi:[1,0]
	v_add_f32_e32 v115, 1.0, v115
	v_rcp_f32_e32 v123, v115
	s_nop 0
	v_pk_mul_f32 v[108:109], v[108:109], v[122:123]
	s_nop 0
	v_pk_mul_f32 v[100:101], v[100:101], v[108:109]
	v_pk_mul_f32 v[108:109], v[110:111], v[116:117] op_sel_hi:[1,0]
	s_nop 0
	v_mul_f32_e32 v110, 0xbfb8aa3b, v108
	v_mul_f32_e32 v111, 0xbfb8aa3b, v109
	v_exp_f32_e32 v110, v110
	v_exp_f32_e32 v111, v111
	v_add_f32_e32 v110, 1.0, v110
	v_add_f32_e32 v111, 1.0, v111
	v_rcp_f32_e32 v110, v110
	v_rcp_f32_e32 v111, v111
	s_nop 0
	v_pk_mul_f32 v[108:109], v[108:109], v[110:111]
	s_nop 0
	v_pk_mul_f32 v[102:103], v[102:103], v[108:109]
	v_mul_f32_e32 v108, 0xbfb8aa3b, v104
	v_mul_f32_e32 v109, 0xbfb8aa3b, v105
	v_exp_f32_e32 v108, v108
	v_exp_f32_e32 v109, v109
	v_add_f32_e32 v108, 1.0, v108
	v_add_f32_e32 v109, 1.0, v109
	v_rcp_f32_e32 v108, v108
	v_rcp_f32_e32 v109, v109
	s_nop 0
	v_pk_mul_f32 v[104:105], v[104:105], v[108:109]
	s_nop 0
	v_pk_mul_f32 v[104:105], v[96:97], v[104:105]
	v_pk_mul_f32 v[96:97], v[106:107], v[116:117] op_sel_hi:[1,0]
	s_nop 0
	v_mul_f32_e32 v106, 0xbfb8aa3b, v96
	v_mul_f32_e32 v107, 0xbfb8aa3b, v97
	v_exp_f32_e32 v106, v106
	v_exp_f32_e32 v107, v107
	v_add_f32_e32 v106, 1.0, v106
	v_add_f32_e32 v107, 1.0, v107
	v_rcp_f32_e32 v106, v106
	v_rcp_f32_e32 v107, v107
	s_nop 0
	v_pk_mul_f32 v[96:97], v[96:97], v[106:107]
	s_nop 0
	v_pk_mul_f32 v[106:107], v[98:99], v[96:97]
	v_cvt_pk_bf16_f32 v96, v100, v101
	v_mad_i64_i32 v[100:101], s[0:1], v114, s92, v[118:119]
	v_cvt_pk_bf16_f32 v97, v102, v103
	v_cvt_pk_bf16_f32 v98, v104, v105
	v_cvt_pk_bf16_f32 v99, v106, v107
	v_lshl_add_u64 v[100:101], v[100:101], 0, v[120:121]
	global_store_dwordx4 v[100:101], v[96:99], off
	s_nop 1
	v_or_b32_e32 v96, 32, v136
	v_ashrrev_i32_e32 v97, 31, v96
	v_lshl_add_u64 v[98:99], v[96:97], 4, s[18:19]
	s_waitcnt vmcnt(7)
; __device__ __forceinline__ u32x4 pack8(const f32x4 a, const f32x4 b) { u32x4 w; w.x = cvt_pk_bf16(a[0], a[1]); w.y = cvt_pk_bf16(a[2], a[3]); w.z = cvt_pk_bf16(b[0], b[1]); w.w = cvt_pk_bf16(b[2], b[3]); return w; }
; __device__ __forceinline__ float sigm(float g) { return __builtin_amdgcn_rcpf(1.0f + __builtin_amdgcn_exp2f(-1.4426950408889634f * g)); }
;     __device__ __forceinline__ void operator()(const f32x4 (&acc)[2][2][4][2], const Unit& u, int wr, int wc, int fr, int fq) const {
;     ...
;             for (int m = 0; m < 4; ++m) { if (m == 0) asm volatile("" ::: "memory"); const int row = row0 + ai * HALF + m * 16; const float rs = rstd_of(ssq, row);
;                 f32x4 o[2];
; #pragma unroll
;                 for (int n = 0; n < 2; ++n) { const f32x4 g = acc[ai][0][m][n] * rs, up = acc[ai][1][m][n] * rs;
; #pragma unroll
;                     for (int e = 0; e < 4; ++e) o[n][e] = g[e] * sigm(g[e]) * up[e]; }
;                 *(u32x4*)(O + (size_t)row * 2816 + col0) = pack8(o[0], o[1]); }
	v_mov_b64_e32 v[98:99], v[158:159]
	v_mov_b64_e32 v[100:101], v[160:161]
	v_mov_b32_e32 v102, v99
	v_mov_b32_e32 v103, v100
	v_mov_b32_e32 v99, v101
	v_pk_add_f32 v[98:99], v[102:103], v[98:99]
	s_nop 0
	v_add_f32_e32 v97, v98, v99
	v_fmamk_f32 v97, v97, 0x3a800000, v231
	v_rsq_f32_e32 v98, v97
	s_nop 0
	v_pk_mul_f32 v[92:93], v[92:93], v[98:99] op_sel_hi:[1,0]
	s_nop 0
	v_mul_f32_e32 v97, 0xbfb8aa3b, v92
	v_exp_f32_e32 v97, v97
	v_pk_mul_f32 v[84:85], v[84:85], v[98:99] op_sel_hi:[1,0]
	v_pk_mul_f32 v[86:87], v[86:87], v[98:99] op_sel_hi:[1,0]
	v_pk_mul_f32 v[88:89], v[88:89], v[98:99] op_sel_hi:[1,0]
	v_add_f32_e32 v97, 1.0, v97
	v_rcp_f32_e32 v100, v97
	v_mul_f32_e32 v97, 0xbfb8aa3b, v93
	v_exp_f32_e32 v97, v97
	v_pk_mul_f32 v[80:81], v[80:81], v[98:99] op_sel_hi:[1,0]
	v_pk_mul_f32 v[82:83], v[82:83], v[98:99] op_sel_hi:[1,0]
	v_add_f32_e32 v97, 1.0, v97
	v_rcp_f32_e32 v101, v97
	s_nop 0
	v_pk_mul_f32 v[92:93], v[92:93], v[100:101]
	s_nop 0
	v_pk_mul_f32 v[84:85], v[84:85], v[92:93]
	v_pk_mul_f32 v[92:93], v[94:95], v[98:99] op_sel_hi:[1,0]
	s_nop 0
	v_mul_f32_e32 v94, 0xbfb8aa3b, v92
	v_mul_f32_e32 v95, 0xbfb8aa3b, v93
	v_exp_f32_e32 v94, v94
	v_exp_f32_e32 v95, v95
	v_add_f32_e32 v94, 1.0, v94
	v_add_f32_e32 v95, 1.0, v95
	v_rcp_f32_e32 v94, v94
	v_rcp_f32_e32 v95, v95
	s_nop 0
	v_pk_mul_f32 v[92:93], v[92:93], v[94:95]
	s_nop 0
	v_pk_mul_f32 v[86:87], v[86:87], v[92:93]
	v_mul_f32_e32 v92, 0xbfb8aa3b, v88
	v_mul_f32_e32 v93, 0xbfb8aa3b, v89
	v_exp_f32_e32 v92, v92
	v_exp_f32_e32 v93, v93
	v_add_f32_e32 v92, 1.0, v92
	v_add_f32_e32 v93, 1.0, v93
	v_rcp_f32_e32 v92, v92
	v_rcp_f32_e32 v93, v93
	s_nop 0
	v_pk_mul_f32 v[88:89], v[88:89], v[92:93]
	s_nop 0
	v_pk_mul_f32 v[88:89], v[80:81], v[88:89]
	v_pk_mul_f32 v[80:81], v[90:91], v[98:99] op_sel_hi:[1,0]
	s_nop 0
	v_mul_f32_e32 v90, 0xbfb8aa3b, v80
	v_mul_f32_e32 v91, 0xbfb8aa3b, v81
	v_exp_f32_e32 v90, v90
	v_exp_f32_e32 v91, v91
	v_add_f32_e32 v90, 1.0, v90
	v_add_f32_e32 v91, 1.0, v91
	v_rcp_f32_e32 v90, v90
	v_rcp_f32_e32 v91, v91
	s_nop 0
	v_pk_mul_f32 v[80:81], v[80:81], v[90:91]
	s_nop 0
	v_pk_mul_f32 v[90:91], v[82:83], v[80:81]
	v_cvt_pk_bf16_f32 v80, v84, v85
	v_mad_i64_i32 v[84:85], s[0:1], v96, s92, v[118:119]
	v_cvt_pk_bf16_f32 v81, v86, v87
	v_cvt_pk_bf16_f32 v82, v88, v89
	v_cvt_pk_bf16_f32 v83, v90, v91
	v_lshl_add_u64 v[84:85], v[84:85], 0, v[120:121]
	global_store_dwordx4 v[84:85], v[80:83], off
	s_nop 1
	v_or_b32_e32 v80, 48, v136
	v_ashrrev_i32_e32 v81, 31, v80
	v_lshl_add_u64 v[82:83], v[80:81], 4, s[18:19]
	s_waitcnt vmcnt(7)
	v_mov_b64_e32 v[82:83], v[162:163]
	v_mov_b64_e32 v[84:85], v[164:165]
	v_mov_b32_e32 v86, v83
	v_mov_b32_e32 v87, v84
	v_mov_b32_e32 v83, v85
	v_pk_add_f32 v[82:83], v[86:87], v[82:83]
	s_nop 0
	v_add_f32_e32 v81, v82, v83
	v_fmamk_f32 v81, v81, 0x3a800000, v231
	v_rsq_f32_e32 v82, v81
	s_nop 0
	v_pk_mul_f32 v[76:77], v[76:77], v[82:83] op_sel_hi:[1,0]
	s_nop 0
	v_mul_f32_e32 v81, 0xbfb8aa3b, v76
	v_exp_f32_e32 v81, v81
	v_pk_mul_f32 v[68:69], v[68:69], v[82:83] op_sel_hi:[1,0]
	v_pk_mul_f32 v[70:71], v[70:71], v[82:83] op_sel_hi:[1,0]
	v_pk_mul_f32 v[72:73], v[72:73], v[82:83] op_sel_hi:[1,0]
	v_add_f32_e32 v81, 1.0, v81
	v_rcp_f32_e32 v84, v81
	v_mul_f32_e32 v81, 0xbfb8aa3b, v77
	v_exp_f32_e32 v81, v81
	v_pk_mul_f32 v[64:65], v[64:65], v[82:83] op_sel_hi:[1,0]
	v_pk_mul_f32 v[66:67], v[66:67], v[82:83] op_sel_hi:[1,0]
	v_add_f32_e32 v81, 1.0, v81
	v_rcp_f32_e32 v85, v81
	s_nop 0
	v_pk_mul_f32 v[76:77], v[76:77], v[84:85]
	s_nop 0
	v_pk_mul_f32 v[68:69], v[68:69], v[76:77]
	v_pk_mul_f32 v[76:77], v[78:79], v[82:83] op_sel_hi:[1,0]
	s_nop 0
	v_mul_f32_e32 v78, 0xbfb8aa3b, v76
	v_mul_f32_e32 v79, 0xbfb8aa3b, v77
	v_exp_f32_e32 v78, v78
	v_exp_f32_e32 v79, v79
	v_add_f32_e32 v78, 1.0, v78
	v_add_f32_e32 v79, 1.0, v79
	v_rcp_f32_e32 v78, v78
	v_rcp_f32_e32 v79, v79
	s_nop 0
	v_pk_mul_f32 v[76:77], v[76:77], v[78:79]
	s_nop 0
	v_pk_mul_f32 v[70:71], v[70:71], v[76:77]
	v_mul_f32_e32 v76, 0xbfb8aa3b, v72
	v_mul_f32_e32 v77, 0xbfb8aa3b, v73
	v_exp_f32_e32 v76, v76
	v_exp_f32_e32 v77, v77
	v_add_f32_e32 v76, 1.0, v76
	v_add_f32_e32 v77, 1.0, v77
	v_rcp_f32_e32 v76, v76
	v_rcp_f32_e32 v77, v77
	s_nop 0
	v_pk_mul_f32 v[72:73], v[72:73], v[76:77]
	s_nop 0
	v_pk_mul_f32 v[72:73], v[64:65], v[72:73]
	v_pk_mul_f32 v[64:65], v[74:75], v[82:83] op_sel_hi:[1,0]
	s_nop 0
	v_mul_f32_e32 v74, 0xbfb8aa3b, v64
	v_mul_f32_e32 v75, 0xbfb8aa3b, v65
	v_exp_f32_e32 v74, v74
	v_exp_f32_e32 v75, v75
	v_add_f32_e32 v74, 1.0, v74
	v_add_f32_e32 v75, 1.0, v75
	v_rcp_f32_e32 v74, v74
	v_rcp_f32_e32 v75, v75
	s_nop 0
	v_pk_mul_f32 v[64:65], v[64:65], v[74:75]
	s_nop 0
	v_pk_mul_f32 v[74:75], v[66:67], v[64:65]
	v_cvt_pk_bf16_f32 v64, v68, v69
	v_mad_i64_i32 v[68:69], s[0:1], v80, s92, v[118:119]
	v_cvt_pk_bf16_f32 v65, v70, v71
	v_cvt_pk_bf16_f32 v66, v72, v73
	v_cvt_pk_bf16_f32 v67, v74, v75
	v_lshl_add_u64 v[68:69], v[68:69], 0, v[120:121]
	global_store_dwordx4 v[68:69], v[64:67], off
	s_nop 1
	v_add_u32_e32 v64, 0x80, v136
	v_ashrrev_i32_e32 v65, 31, v64
	v_lshl_add_u64 v[66:67], v[64:65], 4, s[18:19]
	s_waitcnt vmcnt(7)
; __device__ __forceinline__ u32x4 pack8(const f32x4 a, const f32x4 b) { u32x4 w; w.x = cvt_pk_bf16(a[0], a[1]); w.y = cvt_pk_bf16(a[2], a[3]); w.z = cvt_pk_bf16(b[0], b[1]); w.w = cvt_pk_bf16(b[2], b[3]); return w; }
; __device__ __forceinline__ float sigm(float g) { return __builtin_amdgcn_rcpf(1.0f + __builtin_amdgcn_exp2f(-1.4426950408889634f * g)); }
;     __device__ __forceinline__ void operator()(const f32x4 (&acc)[2][2][4][2], const Unit& u, int wr, int wc, int fr, int fq) const {
;     ...
;             for (int m = 0; m < 4; ++m) { if (m == 0) asm volatile("" ::: "memory"); const int row = row0 + ai * HALF + m * 16; const float rs = rstd_of(ssq, row);
;                 f32x4 o[2];
; #pragma unroll
;                 for (int n = 0; n < 2; ++n) { const f32x4 g = acc[ai][0][m][n] * rs, up = acc[ai][1][m][n] * rs;
; #pragma unroll
;                     for (int e = 0; e < 4; ++e) o[n][e] = g[e] * sigm(g[e]) * up[e]; }
;                 *(u32x4*)(O + (size_t)row * 2816 + col0) = pack8(o[0], o[1]); }
	v_mov_b64_e32 v[66:67], v[166:167]
	v_mov_b64_e32 v[68:69], v[168:169]
	v_mov_b32_e32 v70, v67
	v_mov_b32_e32 v71, v68
	v_mov_b32_e32 v67, v69
	v_pk_add_f32 v[66:67], v[70:71], v[66:67]
	s_nop 0
	v_add_f32_e32 v65, v66, v67
	v_fmamk_f32 v65, v65, 0x3a800000, v231
	v_rsq_f32_e32 v66, v65
	s_nop 0
	v_pk_mul_f32 v[60:61], v[60:61], v[66:67] op_sel_hi:[1,0]
	s_nop 0
	v_mul_f32_e32 v65, 0xbfb8aa3b, v60
	v_exp_f32_e32 v65, v65
	v_pk_mul_f32 v[52:53], v[52:53], v[66:67] op_sel_hi:[1,0]
	v_pk_mul_f32 v[54:55], v[54:55], v[66:67] op_sel_hi:[1,0]
	v_pk_mul_f32 v[56:57], v[56:57], v[66:67] op_sel_hi:[1,0]
	v_add_f32_e32 v65, 1.0, v65
	v_rcp_f32_e32 v68, v65
	v_mul_f32_e32 v65, 0xbfb8aa3b, v61
	v_exp_f32_e32 v65, v65
	v_pk_mul_f32 v[48:49], v[48:49], v[66:67] op_sel_hi:[1,0]
	v_pk_mul_f32 v[50:51], v[50:51], v[66:67] op_sel_hi:[1,0]
	v_add_f32_e32 v65, 1.0, v65
	v_rcp_f32_e32 v69, v65
	s_nop 0
	v_pk_mul_f32 v[60:61], v[60:61], v[68:69]
	s_nop 0
	v_pk_mul_f32 v[52:53], v[52:53], v[60:61]
	v_pk_mul_f32 v[60:61], v[62:63], v[66:67] op_sel_hi:[1,0]
	s_nop 0
	v_mul_f32_e32 v62, 0xbfb8aa3b, v60
	v_mul_f32_e32 v63, 0xbfb8aa3b, v61
	v_exp_f32_e32 v62, v62
	v_exp_f32_e32 v63, v63
	v_add_f32_e32 v62, 1.0, v62
	v_add_f32_e32 v63, 1.0, v63
	v_rcp_f32_e32 v62, v62
	v_rcp_f32_e32 v63, v63
	s_nop 0
	v_pk_mul_f32 v[60:61], v[60:61], v[62:63]
	s_nop 0
	v_pk_mul_f32 v[54:55], v[54:55], v[60:61]
	v_mul_f32_e32 v60, 0xbfb8aa3b, v56
	v_mul_f32_e32 v61, 0xbfb8aa3b, v57
	v_exp_f32_e32 v60, v60
	v_exp_f32_e32 v61, v61
	v_add_f32_e32 v60, 1.0, v60
	v_add_f32_e32 v61, 1.0, v61
	v_rcp_f32_e32 v60, v60
	v_rcp_f32_e32 v61, v61
	s_nop 0
	v_pk_mul_f32 v[56:57], v[56:57], v[60:61]
	s_nop 0
	v_pk_mul_f32 v[56:57], v[48:49], v[56:57]
	v_pk_mul_f32 v[48:49], v[58:59], v[66:67] op_sel_hi:[1,0]
	s_nop 0
	v_mul_f32_e32 v58, 0xbfb8aa3b, v48
	v_mul_f32_e32 v59, 0xbfb8aa3b, v49
	v_exp_f32_e32 v58, v58
	v_exp_f32_e32 v59, v59
	v_add_f32_e32 v58, 1.0, v58
	v_add_f32_e32 v59, 1.0, v59
	v_rcp_f32_e32 v58, v58
	v_rcp_f32_e32 v59, v59
	s_nop 0
	v_pk_mul_f32 v[48:49], v[48:49], v[58:59]
	s_nop 0
	v_pk_mul_f32 v[58:59], v[50:51], v[48:49]
	v_cvt_pk_bf16_f32 v48, v52, v53
	v_mad_i64_i32 v[52:53], s[0:1], v64, s92, v[118:119]
	v_cvt_pk_bf16_f32 v49, v54, v55
	v_cvt_pk_bf16_f32 v50, v56, v57
	v_cvt_pk_bf16_f32 v51, v58, v59
	v_lshl_add_u64 v[52:53], v[52:53], 0, v[120:121]
	global_store_dwordx4 v[52:53], v[48:51], off
	s_nop 1
	v_add_u32_e32 v48, 0x90, v136
	v_ashrrev_i32_e32 v49, 31, v48
	v_lshl_add_u64 v[50:51], v[48:49], 4, s[18:19]
	s_waitcnt vmcnt(7)
	v_mov_b64_e32 v[50:51], v[170:171]
	v_mov_b64_e32 v[52:53], v[172:173]
	v_mov_b32_e32 v54, v51
	v_mov_b32_e32 v55, v52
	v_mov_b32_e32 v51, v53
	v_pk_add_f32 v[50:51], v[54:55], v[50:51]
	s_nop 0
	v_add_f32_e32 v49, v50, v51
	v_fmamk_f32 v49, v49, 0x3a800000, v231
	v_rsq_f32_e32 v50, v49
	s_nop 0
	v_pk_mul_f32 v[44:45], v[44:45], v[50:51] op_sel_hi:[1,0]
	s_nop 0
	v_mul_f32_e32 v49, 0xbfb8aa3b, v44
	v_exp_f32_e32 v49, v49
	v_pk_mul_f32 v[36:37], v[36:37], v[50:51] op_sel_hi:[1,0]
	v_pk_mul_f32 v[38:39], v[38:39], v[50:51] op_sel_hi:[1,0]
	v_pk_mul_f32 v[40:41], v[40:41], v[50:51] op_sel_hi:[1,0]
	v_add_f32_e32 v49, 1.0, v49
	v_rcp_f32_e32 v52, v49
	v_mul_f32_e32 v49, 0xbfb8aa3b, v45
	v_exp_f32_e32 v49, v49
	v_pk_mul_f32 v[32:33], v[32:33], v[50:51] op_sel_hi:[1,0]
	v_pk_mul_f32 v[34:35], v[34:35], v[50:51] op_sel_hi:[1,0]
	v_add_f32_e32 v49, 1.0, v49
	v_rcp_f32_e32 v53, v49
	s_nop 0
	v_pk_mul_f32 v[44:45], v[44:45], v[52:53]
	s_nop 0
	v_pk_mul_f32 v[36:37], v[36:37], v[44:45]
	v_pk_mul_f32 v[44:45], v[46:47], v[50:51] op_sel_hi:[1,0]
	s_nop 0
	v_mul_f32_e32 v46, 0xbfb8aa3b, v44
	v_mul_f32_e32 v47, 0xbfb8aa3b, v45
	v_exp_f32_e32 v46, v46
	v_exp_f32_e32 v47, v47
	v_add_f32_e32 v46, 1.0, v46
	v_add_f32_e32 v47, 1.0, v47
	v_rcp_f32_e32 v46, v46
	v_rcp_f32_e32 v47, v47
	s_nop 0
	v_pk_mul_f32 v[44:45], v[44:45], v[46:47]
	s_nop 0
	v_pk_mul_f32 v[38:39], v[38:39], v[44:45]
	v_mul_f32_e32 v44, 0xbfb8aa3b, v40
	v_mul_f32_e32 v45, 0xbfb8aa3b, v41
	v_exp_f32_e32 v44, v44
	v_exp_f32_e32 v45, v45
	v_add_f32_e32 v44, 1.0, v44
	v_add_f32_e32 v45, 1.0, v45
	v_rcp_f32_e32 v44, v44
	v_rcp_f32_e32 v45, v45
	s_nop 0
	v_pk_mul_f32 v[40:41], v[40:41], v[44:45]
	s_nop 0
	v_pk_mul_f32 v[40:41], v[32:33], v[40:41]
	v_pk_mul_f32 v[32:33], v[42:43], v[50:51] op_sel_hi:[1,0]
	s_nop 0
	v_mul_f32_e32 v42, 0xbfb8aa3b, v32
	v_mul_f32_e32 v43, 0xbfb8aa3b, v33
	v_exp_f32_e32 v42, v42
	v_exp_f32_e32 v43, v43
	v_add_f32_e32 v42, 1.0, v42
	v_add_f32_e32 v43, 1.0, v43
	v_rcp_f32_e32 v42, v42
	v_rcp_f32_e32 v43, v43
	s_nop 0
	v_pk_mul_f32 v[32:33], v[32:33], v[42:43]
	s_nop 0
	v_pk_mul_f32 v[42:43], v[34:35], v[32:33]
	v_cvt_pk_bf16_f32 v32, v36, v37
	v_mad_i64_i32 v[36:37], s[0:1], v48, s92, v[118:119]
	v_cvt_pk_bf16_f32 v33, v38, v39
	v_cvt_pk_bf16_f32 v34, v40, v41
	v_cvt_pk_bf16_f32 v35, v42, v43
	v_lshl_add_u64 v[36:37], v[36:37], 0, v[120:121]
	global_store_dwordx4 v[36:37], v[32:35], off
	s_nop 1
	v_add_u32_e32 v32, 0xa0, v136
	v_ashrrev_i32_e32 v33, 31, v32
	v_lshl_add_u64 v[34:35], v[32:33], 4, s[18:19]
	s_waitcnt vmcnt(7)
; __device__ __forceinline__ u32x4 pack8(const f32x4 a, const f32x4 b) { u32x4 w; w.x = cvt_pk_bf16(a[0], a[1]); w.y = cvt_pk_bf16(a[2], a[3]); w.z = cvt_pk_bf16(b[0], b[1]); w.w = cvt_pk_bf16(b[2], b[3]); return w; }
; __device__ __forceinline__ float sigm(float g) { return __builtin_amdgcn_rcpf(1.0f + __builtin_amdgcn_exp2f(-1.4426950408889634f * g)); }
;     __device__ __forceinline__ void operator()(const f32x4 (&acc)[2][2][4][2], const Unit& u, int wr, int wc, int fr, int fq) const {
;     ...
;             for (int m = 0; m < 4; ++m) { if (m == 0) asm volatile("" ::: "memory"); const int row = row0 + ai * HALF + m * 16; const float rs = rstd_of(ssq, row);
;                 f32x4 o[2];
; #pragma unroll
;                 for (int n = 0; n < 2; ++n) { const f32x4 g = acc[ai][0][m][n] * rs, up = acc[ai][1][m][n] * rs;
; #pragma unroll
;                     for (int e = 0; e < 4; ++e) o[n][e] = g[e] * sigm(g[e]) * up[e]; }
;                 *(u32x4*)(O + (size_t)row * 2816 + col0) = pack8(o[0], o[1]); }
; template <class Epi, class Sched, bool ALIGN_EPI = false, bool SP2 = false>
; __device__ __forceinline__ void gemm_phase(PG8_LAS unsigned char* lds, const Gemm g, const Sched& S, const Epi& E) {
;     ...
;         if constexpr (!Epi::AFTER_DRAIN) { E(acc, cur, wr, wc, fr, fq); S.done(cur); }
;         if (!has_next) break;
	v_mov_b64_e32 v[34:35], v[174:175]
	v_mov_b64_e32 v[36:37], v[176:177]
	v_mov_b32_e32 v38, v35
	v_mov_b32_e32 v39, v36
	v_mov_b32_e32 v35, v37
	v_pk_add_f32 v[34:35], v[38:39], v[34:35]
	s_nop 0
	v_add_f32_e32 v33, v34, v35
	v_fmamk_f32 v33, v33, 0x3a800000, v231
	v_rsq_f32_e32 v34, v33
	s_nop 0
	v_pk_mul_f32 v[28:29], v[28:29], v[34:35] op_sel_hi:[1,0]
	s_nop 0
	v_mul_f32_e32 v33, 0xbfb8aa3b, v28
	v_exp_f32_e32 v33, v33
	v_pk_mul_f32 v[20:21], v[20:21], v[34:35] op_sel_hi:[1,0]
	v_pk_mul_f32 v[22:23], v[22:23], v[34:35] op_sel_hi:[1,0]
	v_pk_mul_f32 v[24:25], v[24:25], v[34:35] op_sel_hi:[1,0]
	v_add_f32_e32 v33, 1.0, v33
	v_rcp_f32_e32 v36, v33
	v_mul_f32_e32 v33, 0xbfb8aa3b, v29
	v_exp_f32_e32 v33, v33
	v_pk_mul_f32 v[16:17], v[16:17], v[34:35] op_sel_hi:[1,0]
	v_pk_mul_f32 v[18:19], v[18:19], v[34:35] op_sel_hi:[1,0]
	v_add_f32_e32 v33, 1.0, v33
	v_rcp_f32_e32 v37, v33
	s_nop 0
	v_pk_mul_f32 v[28:29], v[28:29], v[36:37]
	s_nop 0
	v_pk_mul_f32 v[20:21], v[20:21], v[28:29]
	v_pk_mul_f32 v[28:29], v[30:31], v[34:35] op_sel_hi:[1,0]
	s_nop 0
	v_mul_f32_e32 v30, 0xbfb8aa3b, v28
	v_mul_f32_e32 v31, 0xbfb8aa3b, v29
	v_exp_f32_e32 v30, v30
	v_exp_f32_e32 v31, v31
	v_add_f32_e32 v30, 1.0, v30
	v_add_f32_e32 v31, 1.0, v31
	v_rcp_f32_e32 v30, v30
	v_rcp_f32_e32 v31, v31
	s_nop 0
	v_pk_mul_f32 v[28:29], v[28:29], v[30:31]
	s_nop 0
	v_pk_mul_f32 v[22:23], v[22:23], v[28:29]
	v_mul_f32_e32 v28, 0xbfb8aa3b, v24
	v_mul_f32_e32 v29, 0xbfb8aa3b, v25
	v_exp_f32_e32 v28, v28
	v_exp_f32_e32 v29, v29
	v_add_f32_e32 v28, 1.0, v28
	v_add_f32_e32 v29, 1.0, v29
	v_rcp_f32_e32 v28, v28
	v_rcp_f32_e32 v29, v29
	s_nop 0
	v_pk_mul_f32 v[24:25], v[24:25], v[28:29]
	s_nop 0
	v_pk_mul_f32 v[24:25], v[16:17], v[24:25]
	v_pk_mul_f32 v[16:17], v[26:27], v[34:35] op_sel_hi:[1,0]
	s_nop 0
	v_mul_f32_e32 v26, 0xbfb8aa3b, v16
	v_mul_f32_e32 v27, 0xbfb8aa3b, v17
	v_exp_f32_e32 v26, v26
	v_exp_f32_e32 v27, v27
	v_add_f32_e32 v26, 1.0, v26
	v_add_f32_e32 v27, 1.0, v27
	v_rcp_f32_e32 v26, v26
	v_rcp_f32_e32 v27, v27
	s_nop 0
	v_pk_mul_f32 v[16:17], v[16:17], v[26:27]
	s_nop 0
	v_pk_mul_f32 v[26:27], v[18:19], v[16:17]
	v_cvt_pk_bf16_f32 v16, v20, v21
	v_mad_i64_i32 v[20:21], s[0:1], v32, s92, v[118:119]
	v_cvt_pk_bf16_f32 v17, v22, v23
	v_cvt_pk_bf16_f32 v18, v24, v25
	v_cvt_pk_bf16_f32 v19, v26, v27
	v_lshl_add_u64 v[20:21], v[20:21], 0, v[120:121]
	global_store_dwordx4 v[20:21], v[16:19], off
	s_nop 1
	v_add_u32_e32 v16, 0xb0, v136
	v_ashrrev_i32_e32 v17, 31, v16
	v_lshl_add_u64 v[18:19], v[16:17], 4, s[18:19]
	s_waitcnt vmcnt(7)
	v_mov_b64_e32 v[18:19], v[178:179]
	v_mov_b64_e32 v[20:21], v[180:181]
	v_mov_b32_e32 v22, v19
	v_mov_b32_e32 v23, v20
	v_mov_b32_e32 v19, v21
	v_pk_add_f32 v[18:19], v[22:23], v[18:19]
	s_nop 0
	v_add_f32_e32 v17, v18, v19
	v_fmamk_f32 v17, v17, 0x3a800000, v231
	v_rsq_f32_e32 v18, v17
	s_nop 0
	v_pk_mul_f32 v[12:13], v[12:13], v[18:19] op_sel_hi:[1,0]
	s_nop 0
	v_mul_f32_e32 v17, 0xbfb8aa3b, v12
	v_exp_f32_e32 v17, v17
	v_pk_mul_f32 v[4:5], v[4:5], v[18:19] op_sel_hi:[1,0]
	v_pk_mul_f32 v[6:7], v[6:7], v[18:19] op_sel_hi:[1,0]
	v_pk_mul_f32 v[8:9], v[8:9], v[18:19] op_sel_hi:[1,0]
	v_add_f32_e32 v17, 1.0, v17
	v_rcp_f32_e32 v20, v17
	v_mul_f32_e32 v17, 0xbfb8aa3b, v13
	v_exp_f32_e32 v17, v17
	v_pk_mul_f32 v[0:1], v[0:1], v[18:19] op_sel_hi:[1,0]
	v_pk_mul_f32 v[2:3], v[2:3], v[18:19] op_sel_hi:[1,0]
	v_add_f32_e32 v17, 1.0, v17
	v_rcp_f32_e32 v21, v17
	s_nop 0
	v_pk_mul_f32 v[12:13], v[12:13], v[20:21]
	s_nop 0
	v_pk_mul_f32 v[4:5], v[4:5], v[12:13]
	v_pk_mul_f32 v[12:13], v[14:15], v[18:19] op_sel_hi:[1,0]
	s_nop 0
	v_mul_f32_e32 v14, 0xbfb8aa3b, v12
	v_mul_f32_e32 v15, 0xbfb8aa3b, v13
	v_exp_f32_e32 v14, v14
	v_exp_f32_e32 v15, v15
	v_add_f32_e32 v14, 1.0, v14
	v_add_f32_e32 v15, 1.0, v15
	v_rcp_f32_e32 v14, v14
	v_rcp_f32_e32 v15, v15
	s_nop 0
	v_pk_mul_f32 v[12:13], v[12:13], v[14:15]
	s_nop 0
	v_pk_mul_f32 v[6:7], v[6:7], v[12:13]
	v_mul_f32_e32 v12, 0xbfb8aa3b, v8
	v_mul_f32_e32 v13, 0xbfb8aa3b, v9
	v_exp_f32_e32 v12, v12
	v_exp_f32_e32 v13, v13
	v_add_f32_e32 v12, 1.0, v12
	v_add_f32_e32 v13, 1.0, v13
	v_rcp_f32_e32 v12, v12
	v_rcp_f32_e32 v13, v13
	s_nop 0
	v_pk_mul_f32 v[8:9], v[8:9], v[12:13]
	s_nop 0
	v_pk_mul_f32 v[8:9], v[0:1], v[8:9]
	v_pk_mul_f32 v[0:1], v[10:11], v[18:19] op_sel_hi:[1,0]
	s_nop 0
	v_mul_f32_e32 v10, 0xbfb8aa3b, v0
	v_mul_f32_e32 v11, 0xbfb8aa3b, v1
	v_exp_f32_e32 v10, v10
	v_exp_f32_e32 v11, v11
	v_add_f32_e32 v10, 1.0, v10
	v_add_f32_e32 v11, 1.0, v11
	v_rcp_f32_e32 v10, v10
	v_rcp_f32_e32 v11, v11
	s_nop 0
	v_pk_mul_f32 v[0:1], v[0:1], v[10:11]
	s_nop 0
	v_pk_mul_f32 v[10:11], v[2:3], v[0:1]
	v_cvt_pk_bf16_f32 v0, v4, v5
	v_mad_i64_i32 v[4:5], s[0:1], v16, s92, v[118:119]
	v_cvt_pk_bf16_f32 v1, v6, v7
	v_cvt_pk_bf16_f32 v2, v8, v9
	v_cvt_pk_bf16_f32 v3, v10, v11
	v_lshl_add_u64 v[4:5], v[4:5], 0, v[120:121]
	s_mov_b64 s[0:1], -1
	global_store_dwordx4 v[4:5], v[0:3], off
	s_cbranch_vccnz .LBB0_114
	s_andn2_b64 vcc, exec, s[10:11]
	s_cbranch_vccnz .LBB0_113
	s_barrier
	s_branch .LBB0_113

; __device__ __forceinline__ u32x4 pack8(const f32x4 a, const f32x4 b) { u32x4 w; w.x = cvt_pk_bf16(a[0], a[1]); w.y = cvt_pk_bf16(a[2], a[3]); w.z = cvt_pk_bf16(b[0], b[1]); w.w = cvt_pk_bf16(b[2], b[3]); return w; }
;     __device__ __forceinline__ void fused(const f32x4 (&acc)[2][2][4][2], const Unit& u, int wr, int wc, int fr, int fq, PG8_LAS unsigned char* lds, int wid, int lane) const {
;     ...
;         const int row0 = u.pm * BM + wr * 64 + fr, col0 = u.pn * BM + wc * 32 + 8 * fq;
; #pragma unroll
;         for (int ai = 0; ai < 2; ++ai)
; #pragma unroll
;             for (int m = 0; m < 4; ++m) { if ((m & 1) == 0) asm volatile("" ::: "memory"); const int row = row0 + ai * HALF + m * 16; float ss = 0.f;
; #pragma unroll
;                 for (int bj = 0; bj < 2; ++bj) { float* p = X + (size_t)row * 1024 + col0 + bj * HALF; const float* pi = Xin + (size_t)row * 1024 + col0 + bj * HALF;
;                     f32x4 x0 = *(const f32x4*)pi, x1 = *(const f32x4*)(pi + 4);
;                     x0 = x0 + acc[ai][bj][m][0] * scale; x1 = x1 + acc[ai][bj][m][1] * scale;
;                     *(f32x4*)p = x0; *(f32x4*)(p + 4) = x1;
;                     ss += (x0[0] * x0[0] + x0[1] * x0[1]) + (x0[2] * x0[2] + x0[3] * x0[3]) + (x1[0] * x1[0] + x1[1] * x1[1]) + (x1[2] * x1[2] + x1[3] * x1[3]);
;                     if (!last) *(u32x4*)(XB + (size_t)row * 1024 + col0 + bj * HALF) = pack8(x0, x1); }
.LBB0_278:
	s_add_u32 s0, s16, 0x3c00000
	s_addc_u32 s1, s17, 0
	s_lshl_b32 s8, s36, 8
	s_add_i32 s3, s8, s43
	s_lshl_b32 s2, s28, 5
	v_or_b32_e32 v134, s3, v140
	s_lshl_b32 s3, s18, 8
	v_lshrrev_b32_e32 v112, 1, v142
	s_or_b32 s2, s3, s2
	v_and_or_b32 v130, v112, 24, s2
	v_ashrrev_i32_e32 v135, 31, v134
	v_ashrrev_i32_e32 v131, 31, v130
	v_lshlrev_b64 v[138:139], 12, v[134:135]
	v_lshlrev_b64 v[132:133], 2, v[130:131]
	v_lshl_add_u64 v[136:137], s[22:23], 0, v[138:139]
	s_barrier
	v_lshl_add_u64 v[136:137], v[136:137], 0, v[132:133]
	v_lshlrev_b32_e32 v203, 12, v134
	v_lshl_add_u32 v202, v130, 2, v203
	s_mov_b64 s[52:53], s[22:23]
	global_load_dwordx4 v[154:157], v202, s[52:53]
	global_load_dwordx4 v[158:161], v202, s[52:53] offset:16
	global_load_dwordx4 v[162:165], v202, s[52:53] offset:512
	global_load_dwordx4 v[166:169], v202, s[52:53] offset:528
	s_add_u32 s52, s22, 0x10000
	s_addc_u32 s53, s23, 0
	global_load_dwordx4 v[170:173], v202, s[52:53]
	global_load_dwordx4 v[174:177], v202, s[52:53] offset:16
	global_load_dwordx4 v[178:181], v202, s[52:53] offset:512
	global_load_dwordx4 v[182:185], v202, s[52:53] offset:528
	s_add_u32 s52, s22, 0x20000
	s_addc_u32 s53, s23, 0
	global_load_dwordx4 v[186:189], v202, s[52:53]
	global_load_dwordx4 v[190:193], v202, s[52:53] offset:16
	global_load_dwordx4 v[194:197], v202, s[52:53] offset:512
	global_load_dwordx4 v[198:201], v202, s[52:53] offset:528
	v_readlane_b32 s2, v254, 39
	v_readlane_b32 s3, v254, 40
	v_lshlrev_b64 v[152:153], 10, v[134:135]
	v_lshl_add_u64 v[138:139], s[20:21], 0, v[138:139]
	v_cndmask_b32_e64 v112, 0, 1, s[2:3]
	v_cmp_ne_u32_e64 s[6:7], 1, v112
	s_andn2_b64 vcc, exec, s[2:3]
	v_lshl_add_u64 v[140:141], v[138:139], 0, v[132:133]
	v_lshl_add_u64 v[138:139], v[152:153], 1, s[0:1]
	s_waitcnt vmcnt(10)
	v_pk_fma_f32 v[128:129], v[128:129], 0.5, v[156:157] op_sel_hi:[1,0,1]
	v_pk_fma_f32 v[126:127], v[126:127], 0.5, v[154:155] op_sel_hi:[1,0,1]
	v_pk_fma_f32 v[124:125], v[124:125], 0.5, v[160:161] op_sel_hi:[1,0,1]
	v_pk_fma_f32 v[122:123], v[122:123], 0.5, v[158:159] op_sel_hi:[1,0,1]
	global_store_dwordx4 v[140:141], v[126:129], off
	global_store_dwordx4 v[140:141], v[122:125], off offset:16
	s_cbranch_vccnz .LBB0_280
	v_cvt_pk_bf16_f32 v144, v126, v127
	v_cvt_pk_bf16_f32 v145, v128, v129
	v_cvt_pk_bf16_f32 v146, v122, v123
	v_cvt_pk_bf16_f32 v147, v124, v125
	v_lshl_add_u64 v[148:149], v[130:131], 1, v[138:139]
	global_store_dwordx4 v[148:149], v[144:147], off
.LBB0_280:
	s_and_b64 vcc, exec, s[6:7]
	s_waitcnt vmcnt(10)
	v_pk_fma_f32 v[120:121], v[120:121], 0.5, v[164:165] op_sel_hi:[1,0,1]
	v_pk_fma_f32 v[118:119], v[118:119], 0.5, v[162:163] op_sel_hi:[1,0,1]
	v_pk_fma_f32 v[116:117], v[116:117], 0.5, v[168:169] op_sel_hi:[1,0,1]
	v_pk_fma_f32 v[114:115], v[114:115], 0.5, v[166:167] op_sel_hi:[1,0,1]
	s_add_u32 s52, s22, 0x30000
	s_addc_u32 s53, s23, 0
	global_load_dwordx4 v[154:157], v202, s[52:53]
	global_load_dwordx4 v[158:161], v202, s[52:53] offset:16
	global_load_dwordx4 v[162:165], v202, s[52:53] offset:512
	global_load_dwordx4 v[166:169], v202, s[52:53] offset:528
	global_store_dwordx4 v[140:141], v[118:121], off offset:512
	global_store_dwordx4 v[140:141], v[114:117], off offset:528
	s_cbranch_vccnz .LBB0_282
	v_cvt_pk_bf16_f32 v144, v118, v119
	v_cvt_pk_bf16_f32 v145, v120, v121
	v_cvt_pk_bf16_f32 v146, v114, v115
	v_cvt_pk_bf16_f32 v147, v116, v117
	v_lshl_add_u64 v[136:137], v[130:131], 1, v[138:139]
	global_store_dwordx4 v[136:137], v[144:147], off offset:256

; __device__ __forceinline__ u32x4 pack8(const f32x4 a, const f32x4 b) { u32x4 w; w.x = cvt_pk_bf16(a[0], a[1]); w.y = cvt_pk_bf16(a[2], a[3]); w.z = cvt_pk_bf16(b[0], b[1]); w.w = cvt_pk_bf16(b[2], b[3]); return w; }
;     __device__ __forceinline__ void fused(const f32x4 (&acc)[2][2][4][2], const Unit& u, int wr, int wc, int fr, int fq, PG8_LAS unsigned char* lds, int wid, int lane) const {
;     ...
;             for (int m = 0; m < 4; ++m) { if ((m & 1) == 0) asm volatile("" ::: "memory"); const int row = row0 + ai * HALF + m * 16; float ss = 0.f;
; #pragma unroll
;                 for (int bj = 0; bj < 2; ++bj) { float* p = X + (size_t)row * 1024 + col0 + bj * HALF; const float* pi = Xin + (size_t)row * 1024 + col0 + bj * HALF;
;                     f32x4 x0 = *(const f32x4*)pi, x1 = *(const f32x4*)(pi + 4);
;                     x0 = x0 + acc[ai][bj][m][0] * scale; x1 = x1 + acc[ai][bj][m][1] * scale;
;                     *(f32x4*)p = x0; *(f32x4*)(p + 4) = x1;
;                     ss += (x0[0] * x0[0] + x0[1] * x0[1]) + (x0[2] * x0[2] + x0[3] * x0[3]) + (x1[0] * x1[0] + x1[1] * x1[1]) + (x1[2] * x1[2] + x1[3] * x1[3]);
;                     if (!last) *(u32x4*)(XB + (size_t)row * 1024 + col0 + bj * HALF) = pack8(x0, x1); }
.LBB0_284:
	s_or_b64 exec, exec, s[4:5]
	v_or_b32_e32 v114, 16, v134
	s_waitcnt lgkmcnt(0)
	v_ashrrev_i32_e32 v115, 31, v114
	v_lshlrev_b64 v[116:117], 12, v[114:115]
	v_lshl_add_u64 v[118:119], s[22:23], 0, v[116:117]
	v_lshl_add_u64 v[118:119], v[118:119], 0, v[132:133]
	v_lshlrev_b64 v[114:115], 10, v[114:115]
	v_lshl_add_u64 v[116:117], s[20:21], 0, v[116:117]
	s_and_b64 vcc, exec, s[6:7]
	v_lshl_add_u64 v[116:117], v[116:117], 0, v[132:133]
	v_lshl_add_u64 v[114:115], v[114:115], 1, s[0:1]
	s_waitcnt vmcnt(14)
	v_pk_fma_f32 v[110:111], v[110:111], 0.5, v[172:173] op_sel_hi:[1,0,1]
	v_pk_fma_f32 v[108:109], v[108:109], 0.5, v[170:171] op_sel_hi:[1,0,1]
	v_pk_fma_f32 v[106:107], v[106:107], 0.5, v[176:177] op_sel_hi:[1,0,1]
	v_pk_fma_f32 v[104:105], v[104:105], 0.5, v[174:175] op_sel_hi:[1,0,1]
	global_store_dwordx4 v[116:117], v[108:111], off
	global_store_dwordx4 v[116:117], v[104:107], off offset:16
	s_cbranch_vccnz .LBB0_286
	v_cvt_pk_bf16_f32 v124, v108, v109
	v_cvt_pk_bf16_f32 v125, v110, v111
	v_cvt_pk_bf16_f32 v126, v104, v105
	v_cvt_pk_bf16_f32 v127, v106, v107
	v_lshl_add_u64 v[128:129], v[130:131], 1, v[114:115]
	global_store_dwordx4 v[128:129], v[124:127], off
.LBB0_286:
	s_and_b64 vcc, exec, s[6:7]
	s_waitcnt vmcnt(14)
	v_pk_fma_f32 v[102:103], v[102:103], 0.5, v[180:181] op_sel_hi:[1,0,1]
	v_pk_fma_f32 v[100:101], v[100:101], 0.5, v[178:179] op_sel_hi:[1,0,1]
	v_pk_fma_f32 v[98:99], v[98:99], 0.5, v[184:185] op_sel_hi:[1,0,1]
	v_pk_fma_f32 v[96:97], v[96:97], 0.5, v[182:183] op_sel_hi:[1,0,1]
	s_add_u32 s52, s22, 0x80000
	s_addc_u32 s53, s23, 0
	global_load_dwordx4 v[170:173], v202, s[52:53]
	global_load_dwordx4 v[174:177], v202, s[52:53] offset:16
	global_load_dwordx4 v[178:181], v202, s[52:53] offset:512
	global_load_dwordx4 v[182:185], v202, s[52:53] offset:528
	global_store_dwordx4 v[116:117], v[100:103], off offset:512
	global_store_dwordx4 v[116:117], v[96:99], off offset:528
	s_cbranch_vccnz .LBB0_288
	v_cvt_pk_bf16_f32 v116, v100, v101
	v_cvt_pk_bf16_f32 v117, v102, v103
	v_cvt_pk_bf16_f32 v118, v96, v97
	v_cvt_pk_bf16_f32 v119, v98, v99
	v_lshl_add_u64 v[114:115], v[130:131], 1, v[114:115]
	global_store_dwordx4 v[114:115], v[116:119], off offset:256

; __device__ __forceinline__ u32x4 pack8(const f32x4 a, const f32x4 b) { u32x4 w; w.x = cvt_pk_bf16(a[0], a[1]); w.y = cvt_pk_bf16(a[2], a[3]); w.z = cvt_pk_bf16(b[0], b[1]); w.w = cvt_pk_bf16(b[2], b[3]); return w; }
;     __device__ __forceinline__ void fused(const f32x4 (&acc)[2][2][4][2], const Unit& u, int wr, int wc, int fr, int fq, PG8_LAS unsigned char* lds, int wid, int lane) const {
;     ...
;             for (int m = 0; m < 4; ++m) { if ((m & 1) == 0) asm volatile("" ::: "memory"); const int row = row0 + ai * HALF + m * 16; float ss = 0.f;
; #pragma unroll
;                 for (int bj = 0; bj < 2; ++bj) { float* p = X + (size_t)row * 1024 + col0 + bj * HALF; const float* pi = Xin + (size_t)row * 1024 + col0 + bj * HALF;
;                     f32x4 x0 = *(const f32x4*)pi, x1 = *(const f32x4*)(pi + 4);
;                     x0 = x0 + acc[ai][bj][m][0] * scale; x1 = x1 + acc[ai][bj][m][1] * scale;
;                     *(f32x4*)p = x0; *(f32x4*)(p + 4) = x1;
;                     ss += (x0[0] * x0[0] + x0[1] * x0[1]) + (x0[2] * x0[2] + x0[3] * x0[3]) + (x1[0] * x1[0] + x1[1] * x1[1]) + (x1[2] * x1[2] + x1[3] * x1[3]);
;                     if (!last) *(u32x4*)(XB + (size_t)row * 1024 + col0 + bj * HALF) = pack8(x0, x1); }
.LBB0_290:
	s_or_b64 exec, exec, s[4:5]
	v_or_b32_e32 v96, 32, v134
	s_waitcnt lgkmcnt(0)
	v_ashrrev_i32_e32 v97, 31, v96
	v_lshlrev_b64 v[98:99], 12, v[96:97]
	v_lshl_add_u64 v[100:101], s[22:23], 0, v[98:99]
	v_lshl_add_u64 v[100:101], v[100:101], 0, v[132:133]
	v_lshlrev_b64 v[96:97], 10, v[96:97]
	v_lshl_add_u64 v[98:99], s[20:21], 0, v[98:99]
	s_and_b64 vcc, exec, s[6:7]
	v_lshl_add_u64 v[98:99], v[98:99], 0, v[132:133]
	v_lshl_add_u64 v[96:97], v[96:97], 1, s[0:1]
	s_waitcnt vmcnt(18)
	v_pk_fma_f32 v[94:95], v[94:95], 0.5, v[188:189] op_sel_hi:[1,0,1]
	v_pk_fma_f32 v[92:93], v[92:93], 0.5, v[186:187] op_sel_hi:[1,0,1]
	v_pk_fma_f32 v[90:91], v[90:91], 0.5, v[192:193] op_sel_hi:[1,0,1]
	v_pk_fma_f32 v[88:89], v[88:89], 0.5, v[190:191] op_sel_hi:[1,0,1]
	global_store_dwordx4 v[98:99], v[92:95], off
	global_store_dwordx4 v[98:99], v[88:91], off offset:16
	s_cbranch_vccnz .LBB0_292
	v_cvt_pk_bf16_f32 v102, v92, v93
	v_cvt_pk_bf16_f32 v103, v94, v95
	v_cvt_pk_bf16_f32 v104, v88, v89
	v_cvt_pk_bf16_f32 v105, v90, v91
	v_lshl_add_u64 v[106:107], v[130:131], 1, v[96:97]
	global_store_dwordx4 v[106:107], v[102:105], off
.LBB0_292:
	s_and_b64 vcc, exec, s[6:7]
	s_waitcnt vmcnt(18)
	v_pk_fma_f32 v[86:87], v[86:87], 0.5, v[196:197] op_sel_hi:[1,0,1]
	v_pk_fma_f32 v[84:85], v[84:85], 0.5, v[194:195] op_sel_hi:[1,0,1]
	v_pk_fma_f32 v[82:83], v[82:83], 0.5, v[200:201] op_sel_hi:[1,0,1]
	v_pk_fma_f32 v[80:81], v[80:81], 0.5, v[198:199] op_sel_hi:[1,0,1]
	s_add_u32 s52, s22, 0x90000
	s_addc_u32 s53, s23, 0
	global_load_dwordx4 v[186:189], v202, s[52:53]
	global_load_dwordx4 v[190:193], v202, s[52:53] offset:16
	global_load_dwordx4 v[194:197], v202, s[52:53] offset:512
	global_load_dwordx4 v[198:201], v202, s[52:53] offset:528
	global_store_dwordx4 v[98:99], v[84:87], off offset:512
	global_store_dwordx4 v[98:99], v[80:83], off offset:528
	s_cbranch_vccnz .LBB0_294
	v_cvt_pk_bf16_f32 v98, v84, v85
	v_cvt_pk_bf16_f32 v99, v86, v87
	v_cvt_pk_bf16_f32 v100, v80, v81
	v_cvt_pk_bf16_f32 v101, v82, v83
	v_lshl_add_u64 v[96:97], v[130:131], 1, v[96:97]
	global_store_dwordx4 v[96:97], v[98:101], off offset:256

; __device__ __forceinline__ u32x4 pack8(const f32x4 a, const f32x4 b) { u32x4 w; w.x = cvt_pk_bf16(a[0], a[1]); w.y = cvt_pk_bf16(a[2], a[3]); w.z = cvt_pk_bf16(b[0], b[1]); w.w = cvt_pk_bf16(b[2], b[3]); return w; }
;     __device__ __forceinline__ void fused(const f32x4 (&acc)[2][2][4][2], const Unit& u, int wr, int wc, int fr, int fq, PG8_LAS unsigned char* lds, int wid, int lane) const {
;     ...
;             for (int m = 0; m < 4; ++m) { if ((m & 1) == 0) asm volatile("" ::: "memory"); const int row = row0 + ai * HALF + m * 16; float ss = 0.f;
; #pragma unroll
;                 for (int bj = 0; bj < 2; ++bj) { float* p = X + (size_t)row * 1024 + col0 + bj * HALF; const float* pi = Xin + (size_t)row * 1024 + col0 + bj * HALF;
;                     f32x4 x0 = *(const f32x4*)pi, x1 = *(const f32x4*)(pi + 4);
;                     x0 = x0 + acc[ai][bj][m][0] * scale; x1 = x1 + acc[ai][bj][m][1] * scale;
;                     *(f32x4*)p = x0; *(f32x4*)(p + 4) = x1;
;                     ss += (x0[0] * x0[0] + x0[1] * x0[1]) + (x0[2] * x0[2] + x0[3] * x0[3]) + (x1[0] * x1[0] + x1[1] * x1[1]) + (x1[2] * x1[2] + x1[3] * x1[3]);
;                     if (!last) *(u32x4*)(XB + (size_t)row * 1024 + col0 + bj * HALF) = pack8(x0, x1); }
.LBB0_296:
	s_or_b64 exec, exec, s[4:5]
	v_or_b32_e32 v80, 48, v134
	s_waitcnt lgkmcnt(0)
	v_ashrrev_i32_e32 v81, 31, v80
	v_lshlrev_b64 v[82:83], 12, v[80:81]
	v_lshl_add_u64 v[84:85], s[22:23], 0, v[82:83]
	v_lshl_add_u64 v[84:85], v[84:85], 0, v[132:133]
	v_lshlrev_b64 v[80:81], 10, v[80:81]
	v_lshl_add_u64 v[82:83], s[20:21], 0, v[82:83]
	s_and_b64 vcc, exec, s[6:7]
	v_lshl_add_u64 v[82:83], v[82:83], 0, v[132:133]
	v_lshl_add_u64 v[80:81], v[80:81], 1, s[0:1]
	s_waitcnt vmcnt(20)
	v_pk_fma_f32 v[78:79], v[78:79], 0.5, v[156:157] op_sel_hi:[1,0,1]
	v_pk_fma_f32 v[76:77], v[76:77], 0.5, v[154:155] op_sel_hi:[1,0,1]
	v_pk_fma_f32 v[74:75], v[74:75], 0.5, v[160:161] op_sel_hi:[1,0,1]
	v_pk_fma_f32 v[72:73], v[72:73], 0.5, v[158:159] op_sel_hi:[1,0,1]
	global_store_dwordx4 v[82:83], v[76:79], off
	global_store_dwordx4 v[82:83], v[72:75], off offset:16
	s_cbranch_vccnz .LBB0_298
	v_cvt_pk_bf16_f32 v86, v76, v77
	v_cvt_pk_bf16_f32 v87, v78, v79
	v_cvt_pk_bf16_f32 v88, v72, v73
	v_cvt_pk_bf16_f32 v89, v74, v75
	v_lshl_add_u64 v[90:91], v[130:131], 1, v[80:81]
	global_store_dwordx4 v[90:91], v[86:89], off
.LBB0_298:
	s_and_b64 vcc, exec, s[6:7]
	s_waitcnt vmcnt(20)
	v_pk_fma_f32 v[70:71], v[70:71], 0.5, v[164:165] op_sel_hi:[1,0,1]
	v_pk_fma_f32 v[68:69], v[68:69], 0.5, v[162:163] op_sel_hi:[1,0,1]
	v_pk_fma_f32 v[66:67], v[66:67], 0.5, v[168:169] op_sel_hi:[1,0,1]
	v_pk_fma_f32 v[64:65], v[64:65], 0.5, v[166:167] op_sel_hi:[1,0,1]
	s_add_u32 s52, s22, 0xa0000
	s_addc_u32 s53, s23, 0
	global_load_dwordx4 v[154:157], v202, s[52:53]
	global_load_dwordx4 v[158:161], v202, s[52:53] offset:16
	global_load_dwordx4 v[162:165], v202, s[52:53] offset:512
	global_load_dwordx4 v[166:169], v202, s[52:53] offset:528
	global_store_dwordx4 v[82:83], v[68:71], off offset:512
	global_store_dwordx4 v[82:83], v[64:67], off offset:528
	s_cbranch_vccnz .LBB0_300
	v_cvt_pk_bf16_f32 v82, v68, v69
	v_cvt_pk_bf16_f32 v83, v70, v71
	v_cvt_pk_bf16_f32 v84, v64, v65
	v_cvt_pk_bf16_f32 v85, v66, v67
	v_lshl_add_u64 v[80:81], v[130:131], 1, v[80:81]
	global_store_dwordx4 v[80:81], v[82:85], off offset:256

; __device__ __forceinline__ u32x4 pack8(const f32x4 a, const f32x4 b) { u32x4 w; w.x = cvt_pk_bf16(a[0], a[1]); w.y = cvt_pk_bf16(a[2], a[3]); w.z = cvt_pk_bf16(b[0], b[1]); w.w = cvt_pk_bf16(b[2], b[3]); return w; }
;     __device__ __forceinline__ void fused(const f32x4 (&acc)[2][2][4][2], const Unit& u, int wr, int wc, int fr, int fq, PG8_LAS unsigned char* lds, int wid, int lane) const {
;     ...
;             for (int m = 0; m < 4; ++m) { if ((m & 1) == 0) asm volatile("" ::: "memory"); const int row = row0 + ai * HALF + m * 16; float ss = 0.f;
; #pragma unroll
;                 for (int bj = 0; bj < 2; ++bj) { float* p = X + (size_t)row * 1024 + col0 + bj * HALF; const float* pi = Xin + (size_t)row * 1024 + col0 + bj * HALF;
;                     f32x4 x0 = *(const f32x4*)pi, x1 = *(const f32x4*)(pi + 4);
;                     x0 = x0 + acc[ai][bj][m][0] * scale; x1 = x1 + acc[ai][bj][m][1] * scale;
;                     *(f32x4*)p = x0; *(f32x4*)(p + 4) = x1;
;                     ss += (x0[0] * x0[0] + x0[1] * x0[1]) + (x0[2] * x0[2] + x0[3] * x0[3]) + (x1[0] * x1[0] + x1[1] * x1[1]) + (x1[2] * x1[2] + x1[3] * x1[3]);
;                     if (!last) *(u32x4*)(XB + (size_t)row * 1024 + col0 + bj * HALF) = pack8(x0, x1); }
.LBB0_302:
	s_or_b64 exec, exec, s[4:5]
	v_add_u32_e32 v64, 0x80, v134
	s_waitcnt lgkmcnt(0)
	v_ashrrev_i32_e32 v65, 31, v64
	v_lshlrev_b64 v[66:67], 12, v[64:65]
	v_lshl_add_u64 v[68:69], s[22:23], 0, v[66:67]
	v_lshl_add_u64 v[68:69], v[68:69], 0, v[132:133]
	v_lshlrev_b64 v[64:65], 10, v[64:65]
	v_lshl_add_u64 v[66:67], s[20:21], 0, v[66:67]
	s_and_b64 vcc, exec, s[6:7]
	v_lshl_add_u64 v[66:67], v[66:67], 0, v[132:133]
	v_lshl_add_u64 v[64:65], v[64:65], 1, s[0:1]
	s_waitcnt vmcnt(20)
	v_pk_fma_f32 v[62:63], v[62:63], 0.5, v[172:173] op_sel_hi:[1,0,1]
	v_pk_fma_f32 v[60:61], v[60:61], 0.5, v[170:171] op_sel_hi:[1,0,1]
	v_pk_fma_f32 v[58:59], v[58:59], 0.5, v[176:177] op_sel_hi:[1,0,1]
	v_pk_fma_f32 v[56:57], v[56:57], 0.5, v[174:175] op_sel_hi:[1,0,1]
	global_store_dwordx4 v[66:67], v[60:63], off
	global_store_dwordx4 v[66:67], v[56:59], off offset:16
	s_cbranch_vccnz .LBB0_304
	v_cvt_pk_bf16_f32 v70, v60, v61
	v_cvt_pk_bf16_f32 v71, v62, v63
	v_cvt_pk_bf16_f32 v72, v56, v57
	v_cvt_pk_bf16_f32 v73, v58, v59
	v_lshl_add_u64 v[74:75], v[130:131], 1, v[64:65]
	global_store_dwordx4 v[74:75], v[70:73], off
.LBB0_304:
	s_and_b64 vcc, exec, s[6:7]
	s_waitcnt vmcnt(20)
	v_pk_fma_f32 v[54:55], v[54:55], 0.5, v[180:181] op_sel_hi:[1,0,1]
	v_pk_fma_f32 v[52:53], v[52:53], 0.5, v[178:179] op_sel_hi:[1,0,1]
	v_pk_fma_f32 v[50:51], v[50:51], 0.5, v[184:185] op_sel_hi:[1,0,1]
	v_pk_fma_f32 v[48:49], v[48:49], 0.5, v[182:183] op_sel_hi:[1,0,1]
	s_add_u32 s52, s22, 0xb0000
	s_addc_u32 s53, s23, 0
	global_load_dwordx4 v[170:173], v202, s[52:53]
	global_load_dwordx4 v[174:177], v202, s[52:53] offset:16
	global_load_dwordx4 v[178:181], v202, s[52:53] offset:512
	global_load_dwordx4 v[182:185], v202, s[52:53] offset:528
	global_store_dwordx4 v[66:67], v[52:55], off offset:512
	global_store_dwordx4 v[66:67], v[48:51], off offset:528
	s_cbranch_vccnz .LBB0_306
	v_cvt_pk_bf16_f32 v66, v52, v53
	v_cvt_pk_bf16_f32 v67, v54, v55
	v_cvt_pk_bf16_f32 v68, v48, v49
	v_cvt_pk_bf16_f32 v69, v50, v51
	v_lshl_add_u64 v[64:65], v[130:131], 1, v[64:65]
	global_store_dwordx4 v[64:65], v[66:69], off offset:256

; __device__ __forceinline__ u32x4 pack8(const f32x4 a, const f32x4 b) { u32x4 w; w.x = cvt_pk_bf16(a[0], a[1]); w.y = cvt_pk_bf16(a[2], a[3]); w.z = cvt_pk_bf16(b[0], b[1]); w.w = cvt_pk_bf16(b[2], b[3]); return w; }
;     __device__ __forceinline__ void fused(const f32x4 (&acc)[2][2][4][2], const Unit& u, int wr, int wc, int fr, int fq, PG8_LAS unsigned char* lds, int wid, int lane) const {
;     ...
;             for (int m = 0; m < 4; ++m) { if ((m & 1) == 0) asm volatile("" ::: "memory"); const int row = row0 + ai * HALF + m * 16; float ss = 0.f;
; #pragma unroll
;                 for (int bj = 0; bj < 2; ++bj) { float* p = X + (size_t)row * 1024 + col0 + bj * HALF; const float* pi = Xin + (size_t)row * 1024 + col0 + bj * HALF;
;                     f32x4 x0 = *(const f32x4*)pi, x1 = *(const f32x4*)(pi + 4);
;                     x0 = x0 + acc[ai][bj][m][0] * scale; x1 = x1 + acc[ai][bj][m][1] * scale;
;                     *(f32x4*)p = x0; *(f32x4*)(p + 4) = x1;
;                     ss += (x0[0] * x0[0] + x0[1] * x0[1]) + (x0[2] * x0[2] + x0[3] * x0[3]) + (x1[0] * x1[0] + x1[1] * x1[1]) + (x1[2] * x1[2] + x1[3] * x1[3]);
;                     if (!last) *(u32x4*)(XB + (size_t)row * 1024 + col0 + bj * HALF) = pack8(x0, x1); }
.LBB0_308:
	s_or_b64 exec, exec, s[4:5]
	v_add_u32_e32 v48, 0x90, v134
	s_waitcnt lgkmcnt(0)
	v_ashrrev_i32_e32 v49, 31, v48
	v_lshlrev_b64 v[50:51], 12, v[48:49]
	v_lshl_add_u64 v[52:53], s[22:23], 0, v[50:51]
	v_lshl_add_u64 v[52:53], v[52:53], 0, v[132:133]
	v_lshlrev_b64 v[48:49], 10, v[48:49]
	v_lshl_add_u64 v[50:51], s[20:21], 0, v[50:51]
	s_and_b64 vcc, exec, s[6:7]
	v_lshl_add_u64 v[50:51], v[50:51], 0, v[132:133]
	v_lshl_add_u64 v[48:49], v[48:49], 1, s[0:1]
	s_waitcnt vmcnt(20)
	v_pk_fma_f32 v[46:47], v[46:47], 0.5, v[188:189] op_sel_hi:[1,0,1]
	v_pk_fma_f32 v[44:45], v[44:45], 0.5, v[186:187] op_sel_hi:[1,0,1]
	v_pk_fma_f32 v[42:43], v[42:43], 0.5, v[192:193] op_sel_hi:[1,0,1]
	v_pk_fma_f32 v[40:41], v[40:41], 0.5, v[190:191] op_sel_hi:[1,0,1]
	global_store_dwordx4 v[50:51], v[44:47], off
	global_store_dwordx4 v[50:51], v[40:43], off offset:16
	s_cbranch_vccnz .LBB0_310
	v_cvt_pk_bf16_f32 v54, v44, v45
	v_cvt_pk_bf16_f32 v55, v46, v47
	v_cvt_pk_bf16_f32 v56, v40, v41
	v_cvt_pk_bf16_f32 v57, v42, v43
	v_lshl_add_u64 v[58:59], v[130:131], 1, v[48:49]
	global_store_dwordx4 v[58:59], v[54:57], off
.LBB0_310:
	s_and_b64 vcc, exec, s[6:7]
	s_waitcnt vmcnt(20)
	v_pk_fma_f32 v[38:39], v[38:39], 0.5, v[196:197] op_sel_hi:[1,0,1]
	v_pk_fma_f32 v[36:37], v[36:37], 0.5, v[194:195] op_sel_hi:[1,0,1]
	v_pk_fma_f32 v[34:35], v[34:35], 0.5, v[200:201] op_sel_hi:[1,0,1]
	v_pk_fma_f32 v[32:33], v[32:33], 0.5, v[198:199] op_sel_hi:[1,0,1]
	global_store_dwordx4 v[50:51], v[36:39], off offset:512
	global_store_dwordx4 v[50:51], v[32:35], off offset:528
	s_cbranch_vccnz .LBB0_312
	v_cvt_pk_bf16_f32 v50, v36, v37
	v_cvt_pk_bf16_f32 v51, v38, v39
	v_cvt_pk_bf16_f32 v52, v32, v33
	v_cvt_pk_bf16_f32 v53, v34, v35
	v_lshl_add_u64 v[48:49], v[130:131], 1, v[48:49]
	global_store_dwordx4 v[48:49], v[50:53], off offset:256

; __device__ __forceinline__ u32x4 pack8(const f32x4 a, const f32x4 b) { u32x4 w; w.x = cvt_pk_bf16(a[0], a[1]); w.y = cvt_pk_bf16(a[2], a[3]); w.z = cvt_pk_bf16(b[0], b[1]); w.w = cvt_pk_bf16(b[2], b[3]); return w; }
;     __device__ __forceinline__ void fused(const f32x4 (&acc)[2][2][4][2], const Unit& u, int wr, int wc, int fr, int fq, PG8_LAS unsigned char* lds, int wid, int lane) const {
;     ...
;             for (int m = 0; m < 4; ++m) { if ((m & 1) == 0) asm volatile("" ::: "memory"); const int row = row0 + ai * HALF + m * 16; float ss = 0.f;
; #pragma unroll
;                 for (int bj = 0; bj < 2; ++bj) { float* p = X + (size_t)row * 1024 + col0 + bj * HALF; const float* pi = Xin + (size_t)row * 1024 + col0 + bj * HALF;
;                     f32x4 x0 = *(const f32x4*)pi, x1 = *(const f32x4*)(pi + 4);
;                     x0 = x0 + acc[ai][bj][m][0] * scale; x1 = x1 + acc[ai][bj][m][1] * scale;
;                     *(f32x4*)p = x0; *(f32x4*)(p + 4) = x1;
;                     ss += (x0[0] * x0[0] + x0[1] * x0[1]) + (x0[2] * x0[2] + x0[3] * x0[3]) + (x1[0] * x1[0] + x1[1] * x1[1]) + (x1[2] * x1[2] + x1[3] * x1[3]);
;                     if (!last) *(u32x4*)(XB + (size_t)row * 1024 + col0 + bj * HALF) = pack8(x0, x1); }
.LBB0_314:
	s_or_b64 exec, exec, s[4:5]
	v_add_u32_e32 v32, 0xa0, v134
	s_waitcnt lgkmcnt(0)
	v_ashrrev_i32_e32 v33, 31, v32
	v_lshlrev_b64 v[34:35], 12, v[32:33]
	v_lshl_add_u64 v[36:37], s[22:23], 0, v[34:35]
	v_lshl_add_u64 v[36:37], v[36:37], 0, v[132:133]
	v_lshlrev_b64 v[32:33], 10, v[32:33]
	v_lshl_add_u64 v[34:35], s[20:21], 0, v[34:35]
	s_and_b64 vcc, exec, s[6:7]
	v_lshl_add_u64 v[34:35], v[34:35], 0, v[132:133]
	v_lshl_add_u64 v[32:33], v[32:33], 1, s[0:1]
	s_waitcnt vmcnt(16)
	v_pk_fma_f32 v[30:31], v[30:31], 0.5, v[156:157] op_sel_hi:[1,0,1]
	v_pk_fma_f32 v[28:29], v[28:29], 0.5, v[154:155] op_sel_hi:[1,0,1]
	v_pk_fma_f32 v[26:27], v[26:27], 0.5, v[160:161] op_sel_hi:[1,0,1]
	v_pk_fma_f32 v[24:25], v[24:25], 0.5, v[158:159] op_sel_hi:[1,0,1]
	global_store_dwordx4 v[34:35], v[28:31], off
	global_store_dwordx4 v[34:35], v[24:27], off offset:16
	s_cbranch_vccnz .LBB0_316
	v_cvt_pk_bf16_f32 v38, v28, v29
	v_cvt_pk_bf16_f32 v39, v30, v31
	v_cvt_pk_bf16_f32 v40, v24, v25
	v_cvt_pk_bf16_f32 v41, v26, v27
	v_lshl_add_u64 v[42:43], v[130:131], 1, v[32:33]
	global_store_dwordx4 v[42:43], v[38:41], off
.LBB0_316:
	s_and_b64 vcc, exec, s[6:7]
	s_waitcnt vmcnt(16)
	v_pk_fma_f32 v[22:23], v[22:23], 0.5, v[164:165] op_sel_hi:[1,0,1]
	v_pk_fma_f32 v[20:21], v[20:21], 0.5, v[162:163] op_sel_hi:[1,0,1]
	v_pk_fma_f32 v[18:19], v[18:19], 0.5, v[168:169] op_sel_hi:[1,0,1]
	v_pk_fma_f32 v[16:17], v[16:17], 0.5, v[166:167] op_sel_hi:[1,0,1]
	global_store_dwordx4 v[34:35], v[20:23], off offset:512
	global_store_dwordx4 v[34:35], v[16:19], off offset:528
	s_cbranch_vccnz .LBB0_318
	v_cvt_pk_bf16_f32 v34, v20, v21
	v_cvt_pk_bf16_f32 v35, v22, v23
	v_cvt_pk_bf16_f32 v36, v16, v17
	v_cvt_pk_bf16_f32 v37, v18, v19
	v_lshl_add_u64 v[32:33], v[130:131], 1, v[32:33]
	global_store_dwordx4 v[32:33], v[34:37], off offset:256

; __device__ __forceinline__ u32x4 pack8(const f32x4 a, const f32x4 b) { u32x4 w; w.x = cvt_pk_bf16(a[0], a[1]); w.y = cvt_pk_bf16(a[2], a[3]); w.z = cvt_pk_bf16(b[0], b[1]); w.w = cvt_pk_bf16(b[2], b[3]); return w; }
;     __device__ __forceinline__ void fused(const f32x4 (&acc)[2][2][4][2], const Unit& u, int wr, int wc, int fr, int fq, PG8_LAS unsigned char* lds, int wid, int lane) const {
;     ...
;             for (int m = 0; m < 4; ++m) { if ((m & 1) == 0) asm volatile("" ::: "memory"); const int row = row0 + ai * HALF + m * 16; float ss = 0.f;
; #pragma unroll
;                 for (int bj = 0; bj < 2; ++bj) { float* p = X + (size_t)row * 1024 + col0 + bj * HALF; const float* pi = Xin + (size_t)row * 1024 + col0 + bj * HALF;
;                     f32x4 x0 = *(const f32x4*)pi, x1 = *(const f32x4*)(pi + 4);
;                     x0 = x0 + acc[ai][bj][m][0] * scale; x1 = x1 + acc[ai][bj][m][1] * scale;
;                     *(f32x4*)p = x0; *(f32x4*)(p + 4) = x1;
;                     ss += (x0[0] * x0[0] + x0[1] * x0[1]) + (x0[2] * x0[2] + x0[3] * x0[3]) + (x1[0] * x1[0] + x1[1] * x1[1]) + (x1[2] * x1[2] + x1[3] * x1[3]);
;                     if (!last) *(u32x4*)(XB + (size_t)row * 1024 + col0 + bj * HALF) = pack8(x0, x1); }
.LBB0_320:
	s_or_b64 exec, exec, s[4:5]
	v_add_u32_e32 v18, 0xb0, v134
	v_ashrrev_i32_e32 v19, 31, v18
	v_lshlrev_b64 v[28:29], 12, v[18:19]
	s_waitcnt lgkmcnt(0)
	v_lshl_add_u64 v[16:17], s[22:23], 0, v[28:29]
	v_lshl_add_u64 v[16:17], v[16:17], 0, v[132:133]
	v_lshlrev_b64 v[30:31], 10, v[18:19]
	v_lshl_add_u64 v[18:19], s[20:21], 0, v[28:29]
	s_and_b64 vcc, exec, s[6:7]
	v_lshl_add_u64 v[18:19], v[18:19], 0, v[132:133]
	s_waitcnt vmcnt(12)
	v_pk_fma_f32 v[14:15], v[14:15], 0.5, v[172:173] op_sel_hi:[1,0,1]
	v_pk_fma_f32 v[12:13], v[12:13], 0.5, v[170:171] op_sel_hi:[1,0,1]
	v_pk_fma_f32 v[10:11], v[10:11], 0.5, v[176:177] op_sel_hi:[1,0,1]
	v_pk_fma_f32 v[8:9], v[8:9], 0.5, v[174:175] op_sel_hi:[1,0,1]
	v_lshl_add_u64 v[20:21], v[30:31], 1, s[0:1]
	global_store_dwordx4 v[18:19], v[12:15], off
	global_store_dwordx4 v[18:19], v[8:11], off offset:16
	s_cbranch_vccnz .LBB0_322
	v_cvt_pk_bf16_f32 v22, v12, v13
	v_cvt_pk_bf16_f32 v23, v14, v15
	v_cvt_pk_bf16_f32 v24, v8, v9
	v_cvt_pk_bf16_f32 v25, v10, v11
	v_lshl_add_u64 v[26:27], v[130:131], 1, v[20:21]
	global_store_dwordx4 v[26:27], v[22:25], off
.LBB0_322:
	s_and_b64 vcc, exec, s[6:7]
	s_waitcnt vmcnt(12)
	v_pk_fma_f32 v[6:7], v[6:7], 0.5, v[180:181] op_sel_hi:[1,0,1]
	v_pk_fma_f32 v[4:5], v[4:5], 0.5, v[178:179] op_sel_hi:[1,0,1]
	v_pk_fma_f32 v[2:3], v[2:3], 0.5, v[184:185] op_sel_hi:[1,0,1]
	v_pk_fma_f32 v[0:1], v[0:1], 0.5, v[182:183] op_sel_hi:[1,0,1]
	global_store_dwordx4 v[18:19], v[4:7], off offset:512
	global_store_dwordx4 v[18:19], v[0:3], off offset:528
	s_cbranch_vccnz .LBB0_324
	v_cvt_pk_bf16_f32 v16, v4, v5
	v_cvt_pk_bf16_f32 v17, v6, v7
	v_cvt_pk_bf16_f32 v18, v0, v1
	v_cvt_pk_bf16_f32 v19, v2, v3
	v_lshl_add_u64 v[20:21], v[130:131], 1, v[20:21]
	global_store_dwordx4 v[20:21], v[16:19], off offset:256

.Lfb_pre:
	v_lshl_add_u64 v[188:189], v[188:189], 0, s[20:21]
	v_lshl_add_u64 v[186:187], v[186:187], 0, s[20:21]
	s_mov_b64 s[0:1], 0x5d60e00
	v_lshl_add_u64 v[188:189], v[188:189], 0, s[0:1]
	s_mov_b64 s[0:1], 0x5cb1200
	v_lshl_add_u64 v[186:187], v[186:187], 0, s[0:1]
	s_nop 0
	v_readfirstlane_b32 s2, v188
	v_readfirstlane_b32 s3, v189
	v_readfirstlane_b32 s26, v186
	v_readfirstlane_b32 s27, v187
	s_nop 1
	v_subrev_u32_e32 v188, s2, v188
	v_subrev_u32_e32 v186, s26, v186
	s_mov_b32 s0, 0
.Lfb_loop:
	v_add_u32_e32 v183, s0, v211
	ds_read_b64_tr_b16 v[178:179], v183 offset:24576
	ds_read_b64_tr_b16 v[180:181], v183 offset:25088
	v_mfma_f32_32x32x16_bf16 v[96:111], v[174:177], v[134:137], v[32:47]
	v_add_f32_e32 v80, v64, v65
	v_add_f32_e32 v80, v66, v80
	v_add_f32_e32 v80, v67, v80
	v_add_f32_e32 v80, v68, v80
	v_add_f32_e32 v80, v69, v80
	v_cvt_pk_bf16_f32 v142, v64, v65
	v_cvt_pk_bf16_f32 v143, v66, v67
	ds_read_b64_tr_b16 v[174:175], v183 offset:28672
	ds_read_b64_tr_b16 v[176:177], v183 offset:29184
	v_add_f32_e32 v64, v70, v80
	v_mfma_f32_32x32x16_bf16 v[80:95], v[170:173], v[134:137], v[32:47]
	v_add_f32_e32 v64, v71, v64
	v_add_f32_e32 v64, v72, v64
	v_add_f32_e32 v126, v73, v64
	v_cvt_pk_bf16_f32 v144, v68, v69
	v_cvt_pk_bf16_f32 v145, v70, v71
	ds_read_b64_tr_b16 v[64:65], v183 offset:25600
	ds_read_b64_tr_b16 v[66:67], v183 offset:26112
	v_mfma_f32_32x32x16_bf16 v[96:111], v[166:169], v[122:125], v[96:111]
	v_add_f32_e32 v68, v74, v126
	v_add_f32_e32 v68, v75, v68
	v_add_f32_e32 v68, v76, v68
	v_add_f32_e32 v126, v77, v68
	v_cvt_pk_bf16_f32 v138, v72, v73
	v_cvt_pk_bf16_f32 v139, v74, v75
	ds_read_b64_tr_b16 v[68:69], v183 offset:29696
	ds_read_b64_tr_b16 v[70:71], v183 offset:30208
	v_mfma_f32_32x32x16_bf16 v[80:95], v[162:165], v[122:125], v[80:95]
	v_add_f32_e32 v72, v78, v126
	v_add_f32_e32 v72, v79, v72
	v_add_f32_e32 v72, v48, v72
	v_add_f32_e32 v126, v49, v72
	v_cvt_pk_bf16_f32 v140, v76, v77
	v_cvt_pk_bf16_f32 v141, v78, v79
	ds_read_b64_tr_b16 v[72:73], v183 offset:26624
	ds_read_b64_tr_b16 v[74:75], v183 offset:27136
	v_mfma_f32_32x32x16_bf16 v[96:111], v[158:161], v[118:121], v[96:111]
	v_add_f32_e32 v76, v50, v126
	v_add_f32_e32 v76, v51, v76
	v_add_f32_e32 v76, v52, v76
	v_add_f32_e32 v76, v53, v76
	v_cvt_pk_bf16_f32 v130, v48, v49
	v_cvt_pk_bf16_f32 v131, v50, v51
	ds_read_b64_tr_b16 v[48:49], v183 offset:30720
	ds_read_b64_tr_b16 v[50:51], v183 offset:31232
	v_mfma_f32_32x32x16_bf16 v[80:95], v[154:157], v[118:121], v[80:95]
	v_add_f32_e32 v76, v54, v76
	v_add_f32_e32 v76, v55, v76
	v_add_f32_e32 v76, v56, v76
	v_add_f32_e32 v76, v57, v76
	v_cvt_pk_bf16_f32 v132, v52, v53
	v_cvt_pk_bf16_f32 v133, v54, v55
	ds_read_b64_tr_b16 v[52:53], v183 offset:27648
	ds_read_b64_tr_b16 v[54:55], v183 offset:28160
	v_mfma_f32_32x32x16_bf16 v[96:111], v[150:153], v[114:117], v[96:111]
	v_add_f32_e32 v76, v58, v76
	v_add_f32_e32 v76, v59, v76
	v_add_f32_e32 v76, v60, v76
	v_add_f32_e32 v76, v61, v76
	v_cvt_pk_bf16_f32 v126, v56, v57
	v_cvt_pk_bf16_f32 v127, v58, v59
	ds_read_b64_tr_b16 v[56:57], v183 offset:31744
	ds_read_b64_tr_b16 v[58:59], v183 offset:32256
	v_mfma_f32_32x32x16_bf16 v[80:95], v[146:149], v[114:117], v[80:95]
	v_add_f32_e32 v76, v62, v76
	v_add_f32_e32 v76, v63, v76
	v_cvt_pk_bf16_f32 v128, v60, v61
	v_cvt_pk_bf16_f32 v129, v62, v63
	s_add_i32 m0, s24, s69
	v_add_f32_e32 v185, v222, v76
	global_load_lds_dwordx4 v188, s[2:3]
	s_add_i32 m0, s13, s70
	s_add_u32 s2, s2, 0x58000
	global_load_lds_dwordx4 v186, s[26:27]
	s_addc_u32 s3, s3, 0
	s_add_u32 s26, s26, 0x58000
	s_addc_u32 s27, s27, 0
	s_waitcnt lgkmcnt(8)
	v_mfma_f32_32x32x16_bf16 v[16:31], v[142:145], v[178:181], v[16:31]
	v_exp_f32_e32 v96, v96
	v_exp_f32_e32 v97, v97
	v_exp_f32_e32 v98, v98
	v_exp_f32_e32 v99, v99
	v_mfma_f32_32x32x16_bf16 v[0:15], v[142:145], v[174:177], v[0:15]
	v_exp_f32_e32 v100, v100
	v_exp_f32_e32 v101, v101
	v_exp_f32_e32 v102, v102
	v_exp_f32_e32 v103, v103
	v_add_u32_e32 v76, s13, v210
	ds_read_b128 v[60:63], v76
	ds_read_b128 v[174:177], v76 offset:512
	v_mfma_f32_32x32x16_bf16 v[16:31], v[138:141], v[64:67], v[16:31]
	v_exp_f32_e32 v104, v104
	v_exp_f32_e32 v105, v105
	v_exp_f32_e32 v106, v106
	v_exp_f32_e32 v107, v107
	ds_read_b128 v[178:181], v76 offset:2048
	ds_read_b128 v[170:173], v76 offset:2560
	v_mfma_f32_32x32x16_bf16 v[0:15], v[138:141], v[68:71], v[0:15]
	v_exp_f32_e32 v108, v108
	v_exp_f32_e32 v109, v109
	v_exp_f32_e32 v110, v110
	v_exp_f32_e32 v111, v111
	ds_read_b128 v[166:169], v76 offset:4096
	ds_read_b128 v[162:165], v76 offset:4608
	s_waitcnt lgkmcnt(6)
	v_mfma_f32_32x32x16_bf16 v[16:31], v[130:133], v[72:75], v[16:31]
	v_exp_f32_e32 v80, v80
	v_exp_f32_e32 v81, v81
	v_exp_f32_e32 v82, v82
	v_exp_f32_e32 v83, v83
	ds_read_b128 v[158:161], v76 offset:6144
	ds_read_b128 v[154:157], v76 offset:6656
	v_mfma_f32_32x32x16_bf16 v[0:15], v[130:133], v[48:51], v[0:15]
	v_exp_f32_e32 v84, v84
	v_exp_f32_e32 v85, v85
	v_exp_f32_e32 v86, v86
	v_exp_f32_e32 v87, v87
	v_mfma_f32_32x32x16_bf16 v[16:31], v[126:129], v[52:55], v[16:31]
	v_exp_f32_e32 v88, v88
	v_exp_f32_e32 v89, v89
	v_exp_f32_e32 v90, v90
	v_exp_f32_e32 v91, v91
	v_mfma_f32_32x32x16_bf16 v[0:15], v[126:129], v[56:59], v[0:15]
	v_exp_f32_e32 v92, v92
	v_exp_f32_e32 v93, v93
	v_exp_f32_e32 v94, v94
	v_exp_f32_e32 v95, v95
	s_waitcnt vmcnt(2) lgkmcnt(0)
	s_barrier
; #define WAIT_BAR(N) asm volatile("s_waitcnt vmcnt(" #N ") lgkmcnt(0)\n\ts_barrier":::"memory")
;   #define RESC() do{ if(resc){ asm volatile("s_waitcnt lgkmcnt(0)":::"memory"); \
;       _Pragma("unroll") for(int d_=0;d_<2;++d_) _Pragma("unroll") for(int r=0;r<16;++r)o[d_][r]*=wsf[crow(r,hi)]; } }while(0)
;   #define ROT() do{sl_prev=sl_cur;sl_cur=sl_next;sl_next=(sl_next==(NSLOT-1)*SLOTB)?0:sl_next+SLOTB;}while(0)
;     ...
;     STEP(pB0,pB1,pA0,pA1,t,true,true,true);     WAIT_BAR(2); RESC(); ROT();
;     STEP(pA0,pA1,pB0,pB1,t+1,true,true,true);   WAIT_BAR(2); RESC(); ROT();
;   }
	s_add_i32 s0, s13, 0x2000
	s_cmpk_lg_i32 s13, 0x4000
	s_cselect_b32 s72, s0, 0
	v_add_u32_e32 v196, s24, v211
	ds_read_b64_tr_b16 v[150:151], v196 offset:24576
	ds_read_b64_tr_b16 v[152:153], v196 offset:25088
	v_mfma_f32_32x32x16_bf16 v[64:79], v[60:63], v[134:137], v[32:47]
	v_add_f32_e32 v48, v96, v97
	v_add_f32_e32 v48, v98, v48
	v_add_f32_e32 v48, v99, v48
	v_add_f32_e32 v48, v100, v48
	v_add_f32_e32 v48, v101, v48
	v_cvt_pk_bf16_f32 v142, v96, v97
	v_cvt_pk_bf16_f32 v143, v98, v99
	ds_read_b64_tr_b16 v[146:147], v196 offset:28672
	ds_read_b64_tr_b16 v[148:149], v196 offset:29184
	v_add_f32_e32 v48, v102, v48
	v_add_f32_e32 v48, v103, v48
	v_add_f32_e32 v48, v104, v48
	v_add_f32_e32 v126, v105, v48
	v_mfma_f32_32x32x16_bf16 v[48:63], v[174:177], v[134:137], v[32:47]
	v_cvt_pk_bf16_f32 v144, v100, v101
	v_cvt_pk_bf16_f32 v145, v102, v103
	ds_read_b64_tr_b16 v[96:97], v196 offset:25600
	ds_read_b64_tr_b16 v[98:99], v196 offset:26112
	v_mfma_f32_32x32x16_bf16 v[64:79], v[178:181], v[122:125], v[64:79]
	v_add_f32_e32 v100, v106, v126
	v_add_f32_e32 v100, v107, v100
	v_add_f32_e32 v100, v108, v100
	v_add_f32_e32 v126, v109, v100
	v_cvt_pk_bf16_f32 v138, v104, v105
	v_cvt_pk_bf16_f32 v139, v106, v107
	ds_read_b64_tr_b16 v[100:101], v196 offset:29696
	ds_read_b64_tr_b16 v[102:103], v196 offset:30208
	v_mfma_f32_32x32x16_bf16 v[48:63], v[170:173], v[122:125], v[48:63]
	v_add_f32_e32 v104, v110, v126
	v_add_f32_e32 v104, v111, v104
	v_add_f32_e32 v104, v80, v104
	v_add_f32_e32 v126, v81, v104
	v_cvt_pk_bf16_f32 v140, v108, v109
	v_cvt_pk_bf16_f32 v141, v110, v111
	ds_read_b64_tr_b16 v[104:105], v196 offset:26624
	ds_read_b64_tr_b16 v[106:107], v196 offset:27136
	v_mfma_f32_32x32x16_bf16 v[64:79], v[166:169], v[118:121], v[64:79]
	v_add_f32_e32 v108, v82, v126
	v_add_f32_e32 v108, v83, v108
	v_add_f32_e32 v108, v84, v108
	v_add_f32_e32 v108, v85, v108
	v_cvt_pk_bf16_f32 v130, v80, v81
	v_cvt_pk_bf16_f32 v131, v82, v83
	ds_read_b64_tr_b16 v[80:81], v196 offset:30720
	ds_read_b64_tr_b16 v[82:83], v196 offset:31232
	v_mfma_f32_32x32x16_bf16 v[48:63], v[162:165], v[118:121], v[48:63]
	v_add_f32_e32 v108, v86, v108
	v_add_f32_e32 v108, v87, v108
	v_add_f32_e32 v108, v88, v108
	v_add_f32_e32 v108, v89, v108
	v_cvt_pk_bf16_f32 v132, v84, v85
	v_cvt_pk_bf16_f32 v133, v86, v87
	ds_read_b64_tr_b16 v[84:85], v196 offset:27648
	ds_read_b64_tr_b16 v[86:87], v196 offset:28160
	v_mfma_f32_32x32x16_bf16 v[64:79], v[158:161], v[114:117], v[64:79]
	v_add_f32_e32 v108, v90, v108
	v_add_f32_e32 v108, v91, v108
	v_add_f32_e32 v108, v92, v108
	v_add_f32_e32 v108, v93, v108
	v_cvt_pk_bf16_f32 v126, v88, v89
	v_cvt_pk_bf16_f32 v127, v90, v91
	ds_read_b64_tr_b16 v[88:89], v196 offset:31744
	ds_read_b64_tr_b16 v[90:91], v196 offset:32256
	v_mfma_f32_32x32x16_bf16 v[48:63], v[154:157], v[114:117], v[48:63]
	v_add_f32_e32 v108, v94, v108
	v_add_f32_e32 v108, v95, v108
	v_cvt_pk_bf16_f32 v128, v92, v93
	v_cvt_pk_bf16_f32 v129, v94, v95
	s_add_i32 m0, s13, s69
	v_add_f32_e32 v222, v185, v108
	global_load_lds_dwordx4 v188, s[2:3]
	s_add_i32 m0, s72, s70
	s_add_u32 s2, s2, 0x58000
	global_load_lds_dwordx4 v186, s[26:27]
	s_addc_u32 s3, s3, 0
	s_add_u32 s26, s26, 0x58000
	s_addc_u32 s27, s27, 0
	s_waitcnt lgkmcnt(8)
	v_mfma_f32_32x32x16_bf16 v[16:31], v[142:145], v[150:153], v[16:31]
	v_exp_f32_e32 v64, v64
	v_exp_f32_e32 v65, v65
	v_exp_f32_e32 v66, v66
	v_exp_f32_e32 v67, v67
	v_mfma_f32_32x32x16_bf16 v[0:15], v[142:145], v[146:149], v[0:15]
	v_exp_f32_e32 v68, v68
	v_exp_f32_e32 v69, v69
	v_exp_f32_e32 v70, v70
	v_exp_f32_e32 v71, v71
	v_add_u32_e32 v92, s72, v210
	ds_read_b128 v[174:177], v92
	ds_read_b128 v[170:173], v92 offset:512
	v_mfma_f32_32x32x16_bf16 v[16:31], v[138:141], v[96:99], v[16:31]
	v_exp_f32_e32 v72, v72
	v_exp_f32_e32 v73, v73
	v_exp_f32_e32 v74, v74
	v_exp_f32_e32 v75, v75
	ds_read_b128 v[166:169], v92 offset:2048
	ds_read_b128 v[162:165], v92 offset:2560
	v_mfma_f32_32x32x16_bf16 v[0:15], v[138:141], v[100:103], v[0:15]
	v_exp_f32_e32 v76, v76
	v_exp_f32_e32 v77, v77
	v_exp_f32_e32 v78, v78
	v_exp_f32_e32 v79, v79
	ds_read_b128 v[158:161], v92 offset:4096
	ds_read_b128 v[154:157], v92 offset:4608
	s_waitcnt lgkmcnt(6)
	v_mfma_f32_32x32x16_bf16 v[16:31], v[130:133], v[104:107], v[16:31]
	v_exp_f32_e32 v48, v48
	v_exp_f32_e32 v49, v49
	v_exp_f32_e32 v50, v50
	v_exp_f32_e32 v51, v51
	ds_read_b128 v[150:153], v92 offset:6144
	ds_read_b128 v[146:149], v92 offset:6656
	v_mfma_f32_32x32x16_bf16 v[0:15], v[130:133], v[80:83], v[0:15]
	v_exp_f32_e32 v52, v52
	v_exp_f32_e32 v53, v53
	v_exp_f32_e32 v54, v54
	v_exp_f32_e32 v55, v55
	v_mfma_f32_32x32x16_bf16 v[16:31], v[126:129], v[84:87], v[16:31]
	v_exp_f32_e32 v56, v56
	v_exp_f32_e32 v57, v57
	v_exp_f32_e32 v58, v58
	v_exp_f32_e32 v59, v59
	v_mfma_f32_32x32x16_bf16 v[0:15], v[126:129], v[88:91], v[0:15]
	v_exp_f32_e32 v60, v60
	v_exp_f32_e32 v61, v61
	v_exp_f32_e32 v62, v62
	v_exp_f32_e32 v63, v63
	s_waitcnt vmcnt(2) lgkmcnt(0)
	s_barrier
	s_add_i32 s0, s72, 0x2000
	s_cmpk_lg_i32 s72, 0x4000
	s_cselect_b32 s74, s0, 0
	s_add_i32 s0, s75, 2
	s_cmp_ge_u32 s0, s71
	s_cbranch_scc1 .LBB0_1231
	s_mov_b32 s75, s0
	s_mov_b32 s0, s13
	s_mov_b32 s24, s72
	s_mov_b32 s13, s74
	s_branch .Lfb_loop

; __device__ __forceinline__ u32x4 pack8(const f32x4 a, const f32x4 b) { u32x4 w; w.x = cvt_pk_bf16(a[0], a[1]); w.y = cvt_pk_bf16(a[2], a[3]); w.z = cvt_pk_bf16(b[0], b[1]); w.w = cvt_pk_bf16(b[2], b[3]); return w; }
;     __device__ __forceinline__ void fused(const f32x4 (&acc)[2][2][4][2], const Unit& u, int wr, int wc, int fr, int fq, PG8_LAS unsigned char* lds, int wid, int lane) const {
;     ...
;         const int row0 = u.pm * BM + wr * 64 + fr, col0 = u.pn * BM + wc * 32 + 8 * fq;
; #pragma unroll
;         for (int ai = 0; ai < 2; ++ai)
; #pragma unroll
;             for (int m = 0; m < 4; ++m) { if ((m & 1) == 0) asm volatile("" ::: "memory"); const int row = row0 + ai * HALF + m * 16; float ss = 0.f;
; #pragma unroll
;                 for (int bj = 0; bj < 2; ++bj) { float* p = X + (size_t)row * 1024 + col0 + bj * HALF; const float* pi = Xin + (size_t)row * 1024 + col0 + bj * HALF;
;                     f32x4 x0 = *(const f32x4*)pi, x1 = *(const f32x4*)(pi + 4);
;                     x0 = x0 + acc[ai][bj][m][0] * scale; x1 = x1 + acc[ai][bj][m][1] * scale;
;                     *(f32x4*)p = x0; *(f32x4*)(p + 4) = x1;
;                     ss += (x0[0] * x0[0] + x0[1] * x0[1]) + (x0[2] * x0[2] + x0[3] * x0[3]) + (x1[0] * x1[0] + x1[1] * x1[1]) + (x1[2] * x1[2] + x1[3] * x1[3]);
;                     if (!last) *(u32x4*)(XB + (size_t)row * 1024 + col0 + bj * HALF) = pack8(x0, x1); }
;                 ss += __shfl_xor(ss, 16); ss += __shfl_xor(ss, 32);
;                 if (fq == 0 && !last) P[(ai * HALF + wr * 64 + m * 16 + fr) * 4 + wc] = ss; }
.LBB0_1638:
	s_add_u32 s6, s8, 0x3c00000
	s_addc_u32 s7, s9, 0
	s_lshl_b32 s2, s20, 8
	s_add_i32 s1, s2, s49
	s_lshl_b32 s0, s21, 5
	v_or_b32_e32 v134, s1, v144
	s_lshl_b32 s1, s10, 8
	v_lshrrev_b32_e32 v112, 1, v141
	s_or_b32 s0, s1, s0
	v_and_or_b32 v130, v112, 24, s0
	v_ashrrev_i32_e32 v135, 31, v134
	v_ashrrev_i32_e32 v131, 31, v130
	v_lshlrev_b64 v[148:149], 12, v[134:135]
	v_lshlrev_b64 v[132:133], 2, v[130:131]
	v_lshl_add_u64 v[136:137], s[18:19], 0, v[148:149]
	s_barrier
	v_lshl_add_u64 v[150:151], v[136:137], 0, v[132:133]
	v_lshlrev_b32_e32 v203, 12, v134
	v_lshl_add_u32 v202, v130, 2, v203
	s_mov_b64 s[52:53], s[18:19]
	global_load_dwordx4 v[154:157], v202, s[52:53]
	global_load_dwordx4 v[158:161], v202, s[52:53] offset:16
	global_load_dwordx4 v[162:165], v202, s[52:53] offset:512
	global_load_dwordx4 v[166:169], v202, s[52:53] offset:528
	s_add_u32 s52, s18, 0x10000
	s_addc_u32 s53, s19, 0
	global_load_dwordx4 v[170:173], v202, s[52:53]
	global_load_dwordx4 v[174:177], v202, s[52:53] offset:16
	global_load_dwordx4 v[178:181], v202, s[52:53] offset:512
	global_load_dwordx4 v[182:185], v202, s[52:53] offset:528
	s_add_u32 s52, s18, 0x20000
	s_addc_u32 s53, s19, 0
	global_load_dwordx4 v[186:189], v202, s[52:53]
	global_load_dwordx4 v[190:193], v202, s[52:53] offset:16
	global_load_dwordx4 v[194:197], v202, s[52:53] offset:512
	global_load_dwordx4 v[198:201], v202, s[52:53] offset:528
	v_lshlrev_b64 v[152:153], 11, v[134:135]
	v_lshl_add_u64 v[148:149], s[16:17], 0, v[148:149]
	v_lshl_add_u64 v[152:153], s[6:7], 0, v[152:153]
	v_lshl_add_u64 v[148:149], v[148:149], 0, v[132:133]
	v_lshl_add_u64 v[152:153], v[130:131], 1, v[152:153]
	s_lshl_b32 s0, s21, 2
	v_and_b32_e32 v112, 63, v141
	s_add_i32 s0, s0, 0
	v_cmp_gt_u32_e32 vcc, 16, v112
	s_waitcnt vmcnt(10)
	v_pk_add_f32 v[128:129], v[128:129], v[156:157]
	v_pk_add_f32 v[126:127], v[126:127], v[154:155]
	v_pk_add_f32 v[124:125], v[124:125], v[160:161]
	v_pk_add_f32 v[122:123], v[122:123], v[158:159]
	v_cvt_pk_bf16_f32 v136, v126, v127
	v_cvt_pk_bf16_f32 v137, v128, v129
	v_cvt_pk_bf16_f32 v138, v122, v123
	v_cvt_pk_bf16_f32 v139, v124, v125
	global_store_dwordx4 v[148:149], v[126:129], off
	global_store_dwordx4 v[148:149], v[122:125], off offset:16
	global_store_dwordx4 v[152:153], v[136:139], off
	v_mul_f32_e32 v127, v127, v127
	v_mul_f32_e32 v129, v129, v129
	v_mul_f32_e32 v123, v123, v123
	v_fmac_f32_e32 v127, v126, v126
	v_fmac_f32_e32 v129, v128, v128
	v_mul_f32_e32 v125, v125, v125
	v_fmac_f32_e32 v123, v122, v122
	v_add_f32_e32 v122, v127, v129
	v_fmac_f32_e32 v125, v124, v124
	v_add_f32_e32 v122, v123, v122
	v_add_f32_e32 v126, v125, v122
	s_waitcnt vmcnt(11)
	v_pk_add_f32 v[120:121], v[120:121], v[164:165]
	v_pk_add_f32 v[118:119], v[118:119], v[162:163]
	v_pk_add_f32 v[122:123], v[114:115], v[166:167]
	v_mul_f32_e32 v114, v119, v119
	v_mul_f32_e32 v115, v121, v121
	v_pk_add_f32 v[124:125], v[116:117], v[168:169]
	s_add_u32 s52, s18, 0x30000
	s_addc_u32 s53, s19, 0
	global_load_dwordx4 v[154:157], v202, s[52:53]
	global_load_dwordx4 v[158:161], v202, s[52:53] offset:16
	global_load_dwordx4 v[162:165], v202, s[52:53] offset:512
	global_load_dwordx4 v[166:169], v202, s[52:53] offset:528
	v_mul_f32_e32 v116, v123, v123
	v_fmac_f32_e32 v114, v118, v118
	v_fmac_f32_e32 v115, v120, v120
	v_mul_f32_e32 v117, v125, v125
	v_fmac_f32_e32 v116, v122, v122
	v_add_f32_e32 v114, v114, v115
	v_add_f32_e32 v114, v116, v114
	v_fmac_f32_e32 v117, v124, v124
	v_add_f32_e32 v114, v117, v114
	v_add_f32_e32 v114, v126, v114
	ds_bpermute_b32 v115, v143, v114
	global_store_dwordx4 v[148:149], v[118:121], off offset:512
	global_store_dwordx4 v[148:149], v[122:125], off offset:528
	s_waitcnt lgkmcnt(0)
	v_add_f32_e32 v115, v114, v115
	ds_bpermute_b32 v116, v142, v115
	v_cvt_pk_bf16_f32 v118, v118, v119
	v_cvt_pk_bf16_f32 v119, v120, v121
	v_cvt_pk_bf16_f32 v120, v122, v123
	v_cvt_pk_bf16_f32 v121, v124, v125
	v_lshl_add_u32 v114, v140, 4, s0
	global_store_dwordx4 v[152:153], v[118:121], off offset:256
	s_and_saveexec_b64 s[0:1], vcc
	s_cbranch_execz .LBB0_1640
	s_waitcnt lgkmcnt(0)
	v_add_f32_e32 v115, v115, v116
	ds_write_b32 v114, v115
.LBB0_1640:
	s_or_b64 exec, exec, s[0:1]
	v_or_b32_e32 v124, 16, v134
	v_ashrrev_i32_e32 v125, 31, v124
	v_lshlrev_b64 v[126:127], 12, v[124:125]
	s_waitcnt lgkmcnt(0)
	v_lshl_add_u64 v[116:117], s[18:19], 0, v[126:127]
	v_lshl_add_u64 v[128:129], v[116:117], 0, v[132:133]
	v_lshlrev_b64 v[124:125], 11, v[124:125]
	v_lshl_add_u64 v[126:127], s[16:17], 0, v[126:127]
	v_lshl_add_u64 v[124:125], s[6:7], 0, v[124:125]
	v_lshl_add_u64 v[126:127], v[126:127], 0, v[132:133]
	v_lshl_add_u64 v[124:125], v[130:131], 1, v[124:125]
	s_waitcnt vmcnt(16)
	v_pk_add_f32 v[110:111], v[110:111], v[172:173]
	v_pk_add_f32 v[108:109], v[108:109], v[170:171]
	v_pk_add_f32 v[106:107], v[106:107], v[176:177]
	v_pk_add_f32 v[104:105], v[104:105], v[174:175]
	v_cvt_pk_bf16_f32 v116, v108, v109
	v_cvt_pk_bf16_f32 v117, v110, v111
	v_cvt_pk_bf16_f32 v118, v104, v105
	v_cvt_pk_bf16_f32 v119, v106, v107
	global_store_dwordx4 v[126:127], v[108:111], off
	global_store_dwordx4 v[126:127], v[104:107], off offset:16
	global_store_dwordx4 v[124:125], v[116:119], off
	v_mul_f32_e32 v109, v109, v109
	v_mul_f32_e32 v111, v111, v111
	v_mul_f32_e32 v105, v105, v105
	v_fmac_f32_e32 v109, v108, v108
	v_fmac_f32_e32 v111, v110, v110
	v_mul_f32_e32 v107, v107, v107
	v_fmac_f32_e32 v105, v104, v104
	v_add_f32_e32 v104, v109, v111
	v_fmac_f32_e32 v107, v106, v106
	v_add_f32_e32 v104, v105, v104
	v_add_f32_e32 v108, v107, v104
	s_waitcnt vmcnt(17)
	v_pk_add_f32 v[102:103], v[102:103], v[180:181]
	v_pk_add_f32 v[100:101], v[100:101], v[178:179]
	v_pk_add_f32 v[104:105], v[96:97], v[182:183]
	v_mul_f32_e32 v96, v101, v101
	v_mul_f32_e32 v97, v103, v103
	v_pk_add_f32 v[106:107], v[98:99], v[184:185]
	s_add_u32 s52, s18, 0x80000
	s_addc_u32 s53, s19, 0
	global_load_dwordx4 v[170:173], v202, s[52:53]
	global_load_dwordx4 v[174:177], v202, s[52:53] offset:16
	global_load_dwordx4 v[178:181], v202, s[52:53] offset:512
	global_load_dwordx4 v[182:185], v202, s[52:53] offset:528
	v_mul_f32_e32 v98, v105, v105
	v_fmac_f32_e32 v96, v100, v100
	v_fmac_f32_e32 v97, v102, v102
	v_mul_f32_e32 v99, v107, v107
	v_fmac_f32_e32 v98, v104, v104
	v_add_f32_e32 v96, v96, v97
	v_add_f32_e32 v96, v98, v96
	v_fmac_f32_e32 v99, v106, v106
	v_add_f32_e32 v96, v99, v96
	v_add_f32_e32 v96, v108, v96
	ds_bpermute_b32 v97, v143, v96
	global_store_dwordx4 v[126:127], v[100:103], off offset:512
	global_store_dwordx4 v[126:127], v[104:107], off offset:528
	v_cvt_pk_bf16_f32 v98, v100, v101
	v_cvt_pk_bf16_f32 v99, v102, v103
	v_cvt_pk_bf16_f32 v100, v104, v105
	s_waitcnt lgkmcnt(0)
	v_add_f32_e32 v96, v96, v97
	ds_bpermute_b32 v97, v142, v96
	v_cvt_pk_bf16_f32 v101, v106, v107
	global_store_dwordx4 v[124:125], v[98:101], off offset:256
	s_and_saveexec_b64 s[0:1], vcc
	s_cbranch_execz .LBB0_1642
	s_waitcnt lgkmcnt(0)
	v_add_f32_e32 v96, v96, v97
	ds_write_b32 v114, v96 offset:256
; __device__ __forceinline__ u32x4 pack8(const f32x4 a, const f32x4 b) { u32x4 w; w.x = cvt_pk_bf16(a[0], a[1]); w.y = cvt_pk_bf16(a[2], a[3]); w.z = cvt_pk_bf16(b[0], b[1]); w.w = cvt_pk_bf16(b[2], b[3]); return w; }
;     __device__ __forceinline__ void fused(const f32x4 (&acc)[2][2][4][2], const Unit& u, int wr, int wc, int fr, int fq, PG8_LAS unsigned char* lds, int wid, int lane) const {
;     ...
;             for (int m = 0; m < 4; ++m) { if ((m & 1) == 0) asm volatile("" ::: "memory"); const int row = row0 + ai * HALF + m * 16; float ss = 0.f;
; #pragma unroll
;                 for (int bj = 0; bj < 2; ++bj) { float* p = X + (size_t)row * 1024 + col0 + bj * HALF; const float* pi = Xin + (size_t)row * 1024 + col0 + bj * HALF;
;                     f32x4 x0 = *(const f32x4*)pi, x1 = *(const f32x4*)(pi + 4);
;                     x0 = x0 + acc[ai][bj][m][0] * scale; x1 = x1 + acc[ai][bj][m][1] * scale;
;                     *(f32x4*)p = x0; *(f32x4*)(p + 4) = x1;
;                     ss += (x0[0] * x0[0] + x0[1] * x0[1]) + (x0[2] * x0[2] + x0[3] * x0[3]) + (x1[0] * x1[0] + x1[1] * x1[1]) + (x1[2] * x1[2] + x1[3] * x1[3]);
;                     if (!last) *(u32x4*)(XB + (size_t)row * 1024 + col0 + bj * HALF) = pack8(x0, x1); }
;                 ss += __shfl_xor(ss, 16); ss += __shfl_xor(ss, 32);
;                 if (fq == 0 && !last) P[(ai * HALF + wr * 64 + m * 16 + fr) * 4 + wc] = ss; }
.LBB0_1642:
	s_or_b64 exec, exec, s[0:1]
	v_or_b32_e32 v104, 32, v134
	v_ashrrev_i32_e32 v105, 31, v104
	v_lshlrev_b64 v[106:107], 12, v[104:105]
	s_waitcnt lgkmcnt(0)
	v_lshl_add_u64 v[96:97], s[18:19], 0, v[106:107]
	v_lshl_add_u64 v[108:109], v[96:97], 0, v[132:133]
	v_lshlrev_b64 v[104:105], 11, v[104:105]
	v_lshl_add_u64 v[106:107], s[16:17], 0, v[106:107]
	v_lshl_add_u64 v[104:105], s[6:7], 0, v[104:105]
	v_lshl_add_u64 v[106:107], v[106:107], 0, v[132:133]
	v_lshl_add_u64 v[104:105], v[130:131], 1, v[104:105]
	s_waitcnt vmcnt(22)
	v_pk_add_f32 v[94:95], v[94:95], v[188:189]
	v_pk_add_f32 v[92:93], v[92:93], v[186:187]
	v_pk_add_f32 v[90:91], v[90:91], v[192:193]
	v_pk_add_f32 v[88:89], v[88:89], v[190:191]
	v_cvt_pk_bf16_f32 v96, v92, v93
	v_cvt_pk_bf16_f32 v97, v94, v95
	v_cvt_pk_bf16_f32 v98, v88, v89
	v_cvt_pk_bf16_f32 v99, v90, v91
	global_store_dwordx4 v[106:107], v[92:95], off
	global_store_dwordx4 v[106:107], v[88:91], off offset:16
	global_store_dwordx4 v[104:105], v[96:99], off
	v_mul_f32_e32 v93, v93, v93
	v_mul_f32_e32 v95, v95, v95
	v_mul_f32_e32 v89, v89, v89
	v_fmac_f32_e32 v93, v92, v92
	v_fmac_f32_e32 v95, v94, v94
	v_mul_f32_e32 v91, v91, v91
	v_fmac_f32_e32 v89, v88, v88
	v_add_f32_e32 v88, v93, v95
	v_fmac_f32_e32 v91, v90, v90
	v_add_f32_e32 v88, v89, v88
	v_add_f32_e32 v92, v91, v88
	s_waitcnt vmcnt(23)
	v_pk_add_f32 v[86:87], v[86:87], v[196:197]
	v_pk_add_f32 v[84:85], v[84:85], v[194:195]
	v_pk_add_f32 v[88:89], v[80:81], v[198:199]
	v_mul_f32_e32 v80, v85, v85
	v_mul_f32_e32 v81, v87, v87
	v_pk_add_f32 v[90:91], v[82:83], v[200:201]
	s_add_u32 s52, s18, 0x90000
	s_addc_u32 s53, s19, 0
	global_load_dwordx4 v[186:189], v202, s[52:53]
	global_load_dwordx4 v[190:193], v202, s[52:53] offset:16
	global_load_dwordx4 v[194:197], v202, s[52:53] offset:512
	global_load_dwordx4 v[198:201], v202, s[52:53] offset:528
	v_mul_f32_e32 v82, v89, v89
	v_fmac_f32_e32 v80, v84, v84
	v_fmac_f32_e32 v81, v86, v86
	v_mul_f32_e32 v83, v91, v91
	v_fmac_f32_e32 v82, v88, v88
	v_add_f32_e32 v80, v80, v81
	v_add_f32_e32 v80, v82, v80
	v_fmac_f32_e32 v83, v90, v90
	v_add_f32_e32 v80, v83, v80
	v_add_f32_e32 v80, v92, v80
	ds_bpermute_b32 v81, v143, v80
	global_store_dwordx4 v[106:107], v[84:87], off offset:512
	global_store_dwordx4 v[106:107], v[88:91], off offset:528
	v_cvt_pk_bf16_f32 v82, v84, v85
	v_cvt_pk_bf16_f32 v83, v86, v87
	v_cvt_pk_bf16_f32 v84, v88, v89
	s_waitcnt lgkmcnt(0)
	v_add_f32_e32 v80, v80, v81
	ds_bpermute_b32 v81, v142, v80
	v_cvt_pk_bf16_f32 v85, v90, v91
	global_store_dwordx4 v[104:105], v[82:85], off offset:256
	s_and_saveexec_b64 s[0:1], vcc
	s_cbranch_execz .LBB0_1644
	s_waitcnt lgkmcnt(0)
	v_add_f32_e32 v80, v80, v81
	ds_write_b32 v114, v80 offset:512
.LBB0_1644:
	s_or_b64 exec, exec, s[0:1]
	v_or_b32_e32 v88, 48, v134
	v_ashrrev_i32_e32 v89, 31, v88
	v_lshlrev_b64 v[90:91], 12, v[88:89]
	s_waitcnt lgkmcnt(0)
	v_lshl_add_u64 v[80:81], s[18:19], 0, v[90:91]
	v_lshl_add_u64 v[92:93], v[80:81], 0, v[132:133]
	v_lshlrev_b64 v[88:89], 11, v[88:89]
	v_lshl_add_u64 v[90:91], s[16:17], 0, v[90:91]
	v_lshl_add_u64 v[88:89], s[6:7], 0, v[88:89]
	v_lshl_add_u64 v[90:91], v[90:91], 0, v[132:133]
	v_lshl_add_u64 v[88:89], v[130:131], 1, v[88:89]
	s_waitcnt vmcnt(25)
	v_pk_add_f32 v[78:79], v[78:79], v[156:157]
	v_pk_add_f32 v[76:77], v[76:77], v[154:155]
	v_pk_add_f32 v[74:75], v[74:75], v[160:161]
	v_pk_add_f32 v[72:73], v[72:73], v[158:159]
	v_cvt_pk_bf16_f32 v80, v76, v77
	v_cvt_pk_bf16_f32 v81, v78, v79
	v_cvt_pk_bf16_f32 v82, v72, v73
	v_cvt_pk_bf16_f32 v83, v74, v75
	global_store_dwordx4 v[90:91], v[76:79], off
	global_store_dwordx4 v[90:91], v[72:75], off offset:16
	global_store_dwordx4 v[88:89], v[80:83], off
	v_mul_f32_e32 v77, v77, v77
	v_mul_f32_e32 v79, v79, v79
	v_mul_f32_e32 v73, v73, v73
	v_fmac_f32_e32 v77, v76, v76
	v_fmac_f32_e32 v79, v78, v78
	v_mul_f32_e32 v75, v75, v75
	v_fmac_f32_e32 v73, v72, v72
	v_add_f32_e32 v72, v77, v79
	v_fmac_f32_e32 v75, v74, v74
	v_add_f32_e32 v72, v73, v72
	v_add_f32_e32 v76, v75, v72
	s_waitcnt vmcnt(26)
	v_pk_add_f32 v[70:71], v[70:71], v[164:165]
	v_pk_add_f32 v[68:69], v[68:69], v[162:163]
	v_pk_add_f32 v[72:73], v[64:65], v[166:167]
	v_mul_f32_e32 v64, v69, v69
	v_mul_f32_e32 v65, v71, v71
	v_pk_add_f32 v[74:75], v[66:67], v[168:169]
	s_add_u32 s52, s18, 0xa0000
	s_addc_u32 s53, s19, 0
	global_load_dwordx4 v[154:157], v202, s[52:53]
	global_load_dwordx4 v[158:161], v202, s[52:53] offset:16
	global_load_dwordx4 v[162:165], v202, s[52:53] offset:512
	global_load_dwordx4 v[166:169], v202, s[52:53] offset:528
	v_mul_f32_e32 v66, v73, v73
	v_fmac_f32_e32 v64, v68, v68
	v_fmac_f32_e32 v65, v70, v70
	v_mul_f32_e32 v67, v75, v75
	v_fmac_f32_e32 v66, v72, v72
	v_add_f32_e32 v64, v64, v65
	v_add_f32_e32 v64, v66, v64
	v_fmac_f32_e32 v67, v74, v74
	v_add_f32_e32 v64, v67, v64
	v_add_f32_e32 v64, v76, v64
	ds_bpermute_b32 v65, v143, v64
	global_store_dwordx4 v[90:91], v[68:71], off offset:512
	global_store_dwordx4 v[90:91], v[72:75], off offset:528
	v_cvt_pk_bf16_f32 v66, v68, v69
	v_cvt_pk_bf16_f32 v67, v70, v71
	v_cvt_pk_bf16_f32 v68, v72, v73
	s_waitcnt lgkmcnt(0)
	v_add_f32_e32 v64, v64, v65
	ds_bpermute_b32 v65, v142, v64
	v_cvt_pk_bf16_f32 v69, v74, v75
	global_store_dwordx4 v[88:89], v[66:69], off offset:256
	s_and_saveexec_b64 s[0:1], vcc
	s_cbranch_execz .LBB0_1646
	s_waitcnt lgkmcnt(0)
	v_add_f32_e32 v64, v64, v65
	ds_write_b32 v114, v64 offset:768
; __device__ __forceinline__ u32x4 pack8(const f32x4 a, const f32x4 b) { u32x4 w; w.x = cvt_pk_bf16(a[0], a[1]); w.y = cvt_pk_bf16(a[2], a[3]); w.z = cvt_pk_bf16(b[0], b[1]); w.w = cvt_pk_bf16(b[2], b[3]); return w; }
;     __device__ __forceinline__ void fused(const f32x4 (&acc)[2][2][4][2], const Unit& u, int wr, int wc, int fr, int fq, PG8_LAS unsigned char* lds, int wid, int lane) const {
;     ...
;             for (int m = 0; m < 4; ++m) { if ((m & 1) == 0) asm volatile("" ::: "memory"); const int row = row0 + ai * HALF + m * 16; float ss = 0.f;
; #pragma unroll
;                 for (int bj = 0; bj < 2; ++bj) { float* p = X + (size_t)row * 1024 + col0 + bj * HALF; const float* pi = Xin + (size_t)row * 1024 + col0 + bj * HALF;
;                     f32x4 x0 = *(const f32x4*)pi, x1 = *(const f32x4*)(pi + 4);
;                     x0 = x0 + acc[ai][bj][m][0] * scale; x1 = x1 + acc[ai][bj][m][1] * scale;
;                     *(f32x4*)p = x0; *(f32x4*)(p + 4) = x1;
;                     ss += (x0[0] * x0[0] + x0[1] * x0[1]) + (x0[2] * x0[2] + x0[3] * x0[3]) + (x1[0] * x1[0] + x1[1] * x1[1]) + (x1[2] * x1[2] + x1[3] * x1[3]);
;                     if (!last) *(u32x4*)(XB + (size_t)row * 1024 + col0 + bj * HALF) = pack8(x0, x1); }
;                 ss += __shfl_xor(ss, 16); ss += __shfl_xor(ss, 32);
;                 if (fq == 0 && !last) P[(ai * HALF + wr * 64 + m * 16 + fr) * 4 + wc] = ss; }
.LBB0_1646:
	s_or_b64 exec, exec, s[0:1]
	v_add_u32_e32 v72, 0x80, v134
	v_ashrrev_i32_e32 v73, 31, v72
	v_lshlrev_b64 v[74:75], 12, v[72:73]
	s_waitcnt lgkmcnt(0)
	v_lshl_add_u64 v[64:65], s[18:19], 0, v[74:75]
	v_lshl_add_u64 v[76:77], v[64:65], 0, v[132:133]
	v_lshlrev_b64 v[72:73], 11, v[72:73]
	v_lshl_add_u64 v[74:75], s[16:17], 0, v[74:75]
	v_lshl_add_u64 v[72:73], s[6:7], 0, v[72:73]
	v_lshl_add_u64 v[74:75], v[74:75], 0, v[132:133]
	v_lshl_add_u64 v[72:73], v[130:131], 1, v[72:73]
	s_waitcnt vmcnt(25)
	v_pk_add_f32 v[62:63], v[62:63], v[172:173]
	v_pk_add_f32 v[60:61], v[60:61], v[170:171]
	v_pk_add_f32 v[58:59], v[58:59], v[176:177]
	v_pk_add_f32 v[56:57], v[56:57], v[174:175]
	v_cvt_pk_bf16_f32 v64, v60, v61
	v_cvt_pk_bf16_f32 v65, v62, v63
	v_cvt_pk_bf16_f32 v66, v56, v57
	v_cvt_pk_bf16_f32 v67, v58, v59
	global_store_dwordx4 v[74:75], v[60:63], off
	global_store_dwordx4 v[74:75], v[56:59], off offset:16
	global_store_dwordx4 v[72:73], v[64:67], off
	v_mul_f32_e32 v61, v61, v61
	v_mul_f32_e32 v63, v63, v63
	v_mul_f32_e32 v57, v57, v57
	v_fmac_f32_e32 v61, v60, v60
	v_fmac_f32_e32 v63, v62, v62
	v_mul_f32_e32 v59, v59, v59
	v_fmac_f32_e32 v57, v56, v56
	v_add_f32_e32 v56, v61, v63
	v_fmac_f32_e32 v59, v58, v58
	v_add_f32_e32 v56, v57, v56
	v_add_f32_e32 v60, v59, v56
	s_waitcnt vmcnt(26)
	v_pk_add_f32 v[54:55], v[54:55], v[180:181]
	v_pk_add_f32 v[52:53], v[52:53], v[178:179]
	v_pk_add_f32 v[56:57], v[48:49], v[182:183]
	v_mul_f32_e32 v48, v53, v53
	v_mul_f32_e32 v49, v55, v55
	v_pk_add_f32 v[58:59], v[50:51], v[184:185]
	s_add_u32 s52, s18, 0xb0000
	s_addc_u32 s53, s19, 0
	global_load_dwordx4 v[170:173], v202, s[52:53]
	global_load_dwordx4 v[174:177], v202, s[52:53] offset:16
	global_load_dwordx4 v[178:181], v202, s[52:53] offset:512
	global_load_dwordx4 v[182:185], v202, s[52:53] offset:528
	v_mul_f32_e32 v50, v57, v57
	v_fmac_f32_e32 v48, v52, v52
	v_fmac_f32_e32 v49, v54, v54
	v_mul_f32_e32 v51, v59, v59
	v_fmac_f32_e32 v50, v56, v56
	v_add_f32_e32 v48, v48, v49
	v_add_f32_e32 v48, v50, v48
	v_fmac_f32_e32 v51, v58, v58
	v_add_f32_e32 v48, v51, v48
	v_add_f32_e32 v48, v60, v48
	ds_bpermute_b32 v49, v143, v48
	global_store_dwordx4 v[74:75], v[52:55], off offset:512
	global_store_dwordx4 v[74:75], v[56:59], off offset:528
	v_cvt_pk_bf16_f32 v50, v52, v53
	v_cvt_pk_bf16_f32 v51, v54, v55
	v_cvt_pk_bf16_f32 v52, v56, v57
	s_waitcnt lgkmcnt(0)
	v_add_f32_e32 v48, v48, v49
	ds_bpermute_b32 v49, v142, v48
	v_cvt_pk_bf16_f32 v53, v58, v59
	global_store_dwordx4 v[72:73], v[50:53], off offset:256
	s_and_saveexec_b64 s[0:1], vcc
	s_cbranch_execz .LBB0_1648
	s_waitcnt lgkmcnt(0)
	v_add_f32_e32 v48, v48, v49
	ds_write_b32 v114, v48 offset:2048
.LBB0_1648:
	s_or_b64 exec, exec, s[0:1]
	v_add_u32_e32 v56, 0x90, v134
	v_ashrrev_i32_e32 v57, 31, v56
	v_lshlrev_b64 v[58:59], 12, v[56:57]
	s_waitcnt lgkmcnt(0)
	v_lshl_add_u64 v[48:49], s[18:19], 0, v[58:59]
	v_lshl_add_u64 v[60:61], v[48:49], 0, v[132:133]
	v_lshlrev_b64 v[56:57], 11, v[56:57]
	v_lshl_add_u64 v[58:59], s[16:17], 0, v[58:59]
	v_lshl_add_u64 v[56:57], s[6:7], 0, v[56:57]
	v_lshl_add_u64 v[58:59], v[58:59], 0, v[132:133]
	v_lshl_add_u64 v[56:57], v[130:131], 1, v[56:57]
	s_waitcnt vmcnt(25)
	v_pk_add_f32 v[46:47], v[46:47], v[188:189]
	v_pk_add_f32 v[44:45], v[44:45], v[186:187]
	v_pk_add_f32 v[42:43], v[42:43], v[192:193]
	v_pk_add_f32 v[40:41], v[40:41], v[190:191]
	v_cvt_pk_bf16_f32 v48, v44, v45
	v_cvt_pk_bf16_f32 v49, v46, v47
	v_cvt_pk_bf16_f32 v50, v40, v41
	v_cvt_pk_bf16_f32 v51, v42, v43
	global_store_dwordx4 v[58:59], v[44:47], off
	global_store_dwordx4 v[58:59], v[40:43], off offset:16
	global_store_dwordx4 v[56:57], v[48:51], off
	v_mul_f32_e32 v45, v45, v45
	v_mul_f32_e32 v47, v47, v47
	v_mul_f32_e32 v41, v41, v41
	v_fmac_f32_e32 v45, v44, v44
	v_fmac_f32_e32 v47, v46, v46
	v_mul_f32_e32 v43, v43, v43
	v_fmac_f32_e32 v41, v40, v40
	v_add_f32_e32 v40, v45, v47
	v_fmac_f32_e32 v43, v42, v42
	v_add_f32_e32 v40, v41, v40
	v_add_f32_e32 v44, v43, v40
	s_waitcnt vmcnt(26)
	v_pk_add_f32 v[38:39], v[38:39], v[196:197]
	v_pk_add_f32 v[36:37], v[36:37], v[194:195]
	v_pk_add_f32 v[40:41], v[32:33], v[198:199]
	v_mul_f32_e32 v32, v37, v37
	v_mul_f32_e32 v33, v39, v39
	v_pk_add_f32 v[42:43], v[34:35], v[200:201]
	v_mul_f32_e32 v34, v41, v41
	v_fmac_f32_e32 v32, v36, v36
	v_fmac_f32_e32 v33, v38, v38
	v_mul_f32_e32 v35, v43, v43
	v_fmac_f32_e32 v34, v40, v40
	v_add_f32_e32 v32, v32, v33
	v_add_f32_e32 v32, v34, v32
	v_fmac_f32_e32 v35, v42, v42
	v_add_f32_e32 v32, v35, v32
	v_add_f32_e32 v32, v44, v32
	ds_bpermute_b32 v33, v143, v32
	global_store_dwordx4 v[58:59], v[36:39], off offset:512
	global_store_dwordx4 v[58:59], v[40:43], off offset:528
	v_cvt_pk_bf16_f32 v34, v36, v37
	v_cvt_pk_bf16_f32 v35, v38, v39
	v_cvt_pk_bf16_f32 v36, v40, v41
	s_waitcnt lgkmcnt(0)
	v_add_f32_e32 v32, v32, v33
	ds_bpermute_b32 v33, v142, v32
	v_cvt_pk_bf16_f32 v37, v42, v43
	global_store_dwordx4 v[56:57], v[34:37], off offset:256
	s_and_saveexec_b64 s[0:1], vcc
	s_cbranch_execz .LBB0_1650
	s_waitcnt lgkmcnt(0)
	v_add_f32_e32 v32, v32, v33
	ds_write_b32 v114, v32 offset:2304
; __device__ __forceinline__ u32x4 pack8(const f32x4 a, const f32x4 b) { u32x4 w; w.x = cvt_pk_bf16(a[0], a[1]); w.y = cvt_pk_bf16(a[2], a[3]); w.z = cvt_pk_bf16(b[0], b[1]); w.w = cvt_pk_bf16(b[2], b[3]); return w; }
;     __device__ __forceinline__ void fused(const f32x4 (&acc)[2][2][4][2], const Unit& u, int wr, int wc, int fr, int fq, PG8_LAS unsigned char* lds, int wid, int lane) const {
;     ...
;             for (int m = 0; m < 4; ++m) { if ((m & 1) == 0) asm volatile("" ::: "memory"); const int row = row0 + ai * HALF + m * 16; float ss = 0.f;
; #pragma unroll
;                 for (int bj = 0; bj < 2; ++bj) { float* p = X + (size_t)row * 1024 + col0 + bj * HALF; const float* pi = Xin + (size_t)row * 1024 + col0 + bj * HALF;
;                     f32x4 x0 = *(const f32x4*)pi, x1 = *(const f32x4*)(pi + 4);
;                     x0 = x0 + acc[ai][bj][m][0] * scale; x1 = x1 + acc[ai][bj][m][1] * scale;
;                     *(f32x4*)p = x0; *(f32x4*)(p + 4) = x1;
;                     ss += (x0[0] * x0[0] + x0[1] * x0[1]) + (x0[2] * x0[2] + x0[3] * x0[3]) + (x1[0] * x1[0] + x1[1] * x1[1]) + (x1[2] * x1[2] + x1[3] * x1[3]);
;                     if (!last) *(u32x4*)(XB + (size_t)row * 1024 + col0 + bj * HALF) = pack8(x0, x1); }
;                 ss += __shfl_xor(ss, 16); ss += __shfl_xor(ss, 32);
;                 if (fq == 0 && !last) P[(ai * HALF + wr * 64 + m * 16 + fr) * 4 + wc] = ss; }
.LBB0_1650:
	s_or_b64 exec, exec, s[0:1]
	v_add_u32_e32 v40, 0xa0, v134
	v_ashrrev_i32_e32 v41, 31, v40
	v_lshlrev_b64 v[42:43], 12, v[40:41]
	s_waitcnt lgkmcnt(0)
	v_lshl_add_u64 v[32:33], s[18:19], 0, v[42:43]
	v_lshl_add_u64 v[44:45], v[32:33], 0, v[132:133]
	v_lshlrev_b64 v[40:41], 11, v[40:41]
	v_lshl_add_u64 v[42:43], s[16:17], 0, v[42:43]
	v_lshl_add_u64 v[40:41], s[6:7], 0, v[40:41]
	v_lshl_add_u64 v[42:43], v[42:43], 0, v[132:133]
	v_lshl_add_u64 v[40:41], v[130:131], 1, v[40:41]
	s_waitcnt vmcnt(21)
	v_pk_add_f32 v[30:31], v[30:31], v[156:157]
	v_pk_add_f32 v[28:29], v[28:29], v[154:155]
	v_pk_add_f32 v[26:27], v[26:27], v[160:161]
	v_pk_add_f32 v[24:25], v[24:25], v[158:159]
	v_cvt_pk_bf16_f32 v32, v28, v29
	v_cvt_pk_bf16_f32 v33, v30, v31
	v_cvt_pk_bf16_f32 v34, v24, v25
	v_cvt_pk_bf16_f32 v35, v26, v27
	global_store_dwordx4 v[42:43], v[28:31], off
	global_store_dwordx4 v[42:43], v[24:27], off offset:16
	global_store_dwordx4 v[40:41], v[32:35], off
	v_mul_f32_e32 v29, v29, v29
	v_mul_f32_e32 v31, v31, v31
	v_mul_f32_e32 v25, v25, v25
	v_fmac_f32_e32 v29, v28, v28
	v_fmac_f32_e32 v31, v30, v30
	v_mul_f32_e32 v27, v27, v27
	v_fmac_f32_e32 v25, v24, v24
	v_add_f32_e32 v24, v29, v31
	v_fmac_f32_e32 v27, v26, v26
	v_add_f32_e32 v24, v25, v24
	v_add_f32_e32 v28, v27, v24
	s_waitcnt vmcnt(22)
	v_pk_add_f32 v[22:23], v[22:23], v[164:165]
	v_pk_add_f32 v[20:21], v[20:21], v[162:163]
	v_pk_add_f32 v[24:25], v[16:17], v[166:167]
	v_mul_f32_e32 v16, v21, v21
	v_mul_f32_e32 v17, v23, v23
	v_pk_add_f32 v[26:27], v[18:19], v[168:169]
	v_mul_f32_e32 v18, v25, v25
	v_fmac_f32_e32 v16, v20, v20
	v_fmac_f32_e32 v17, v22, v22
	v_mul_f32_e32 v19, v27, v27
	v_fmac_f32_e32 v18, v24, v24
	v_add_f32_e32 v16, v16, v17
	v_add_f32_e32 v16, v18, v16
	v_fmac_f32_e32 v19, v26, v26
	v_add_f32_e32 v16, v19, v16
	v_add_f32_e32 v16, v28, v16
	ds_bpermute_b32 v17, v143, v16
	global_store_dwordx4 v[42:43], v[20:23], off offset:512
	global_store_dwordx4 v[42:43], v[24:27], off offset:528
	v_cvt_pk_bf16_f32 v18, v20, v21
	v_cvt_pk_bf16_f32 v19, v22, v23
	v_cvt_pk_bf16_f32 v20, v24, v25
	s_waitcnt lgkmcnt(0)
	v_add_f32_e32 v16, v16, v17
	ds_bpermute_b32 v17, v142, v16
	v_cvt_pk_bf16_f32 v21, v26, v27
	global_store_dwordx4 v[40:41], v[18:21], off offset:256
	s_and_saveexec_b64 s[0:1], vcc
	s_cbranch_execz .LBB0_1652
	s_waitcnt lgkmcnt(0)
	v_add_f32_e32 v16, v16, v17
	ds_write_b32 v114, v16 offset:2560
.LBB0_1652:
	s_or_b64 exec, exec, s[0:1]
	v_add_u32_e32 v24, 0xb0, v134
	v_ashrrev_i32_e32 v25, 31, v24
	v_lshlrev_b64 v[26:27], 12, v[24:25]
	s_waitcnt lgkmcnt(0)
	v_lshl_add_u64 v[16:17], s[18:19], 0, v[26:27]
	v_lshl_add_u64 v[28:29], v[16:17], 0, v[132:133]
	v_lshlrev_b64 v[24:25], 11, v[24:25]
	v_lshl_add_u64 v[26:27], s[16:17], 0, v[26:27]
	v_lshl_add_u64 v[24:25], s[6:7], 0, v[24:25]
	v_lshl_add_u64 v[26:27], v[26:27], 0, v[132:133]
	v_lshl_add_u64 v[24:25], v[130:131], 1, v[24:25]
	s_waitcnt vmcnt(17)
	v_pk_add_f32 v[14:15], v[14:15], v[172:173]
	v_pk_add_f32 v[12:13], v[12:13], v[170:171]
	v_pk_add_f32 v[10:11], v[10:11], v[176:177]
	v_pk_add_f32 v[8:9], v[8:9], v[174:175]
	v_cvt_pk_bf16_f32 v16, v12, v13
	v_cvt_pk_bf16_f32 v17, v14, v15
	v_cvt_pk_bf16_f32 v18, v8, v9
	v_cvt_pk_bf16_f32 v19, v10, v11
	global_store_dwordx4 v[26:27], v[12:15], off
	global_store_dwordx4 v[26:27], v[8:11], off offset:16
	global_store_dwordx4 v[24:25], v[16:19], off
	v_mul_f32_e32 v13, v13, v13
	v_mul_f32_e32 v15, v15, v15
	v_mul_f32_e32 v9, v9, v9
	v_fmac_f32_e32 v13, v12, v12
	v_fmac_f32_e32 v15, v14, v14
	v_mul_f32_e32 v11, v11, v11
	v_fmac_f32_e32 v9, v8, v8
	v_add_f32_e32 v8, v13, v15
	v_fmac_f32_e32 v11, v10, v10
	v_add_f32_e32 v8, v9, v8
	v_add_f32_e32 v12, v11, v8
	s_waitcnt vmcnt(18)
	v_pk_add_f32 v[6:7], v[6:7], v[180:181]
	v_pk_add_f32 v[4:5], v[4:5], v[178:179]
	v_pk_add_f32 v[8:9], v[0:1], v[182:183]
	v_mul_f32_e32 v0, v5, v5
	v_mul_f32_e32 v1, v7, v7
	v_pk_add_f32 v[10:11], v[2:3], v[184:185]
	v_mul_f32_e32 v2, v9, v9
	v_fmac_f32_e32 v0, v4, v4
	v_fmac_f32_e32 v1, v6, v6
	v_mul_f32_e32 v3, v11, v11
	v_fmac_f32_e32 v2, v8, v8
	v_add_f32_e32 v0, v0, v1
	v_add_f32_e32 v0, v2, v0
	v_fmac_f32_e32 v3, v10, v10
	v_add_f32_e32 v0, v3, v0
	v_add_f32_e32 v0, v12, v0
	ds_bpermute_b32 v1, v143, v0
	global_store_dwordx4 v[26:27], v[4:7], off offset:512
	global_store_dwordx4 v[26:27], v[8:11], off offset:528
	v_cvt_pk_bf16_f32 v2, v4, v5
	v_cvt_pk_bf16_f32 v3, v6, v7
	v_cvt_pk_bf16_f32 v4, v8, v9
	s_waitcnt lgkmcnt(0)
	v_add_f32_e32 v0, v0, v1
	ds_bpermute_b32 v1, v142, v0
	v_cvt_pk_bf16_f32 v5, v10, v11
	global_store_dwordx4 v[24:25], v[2:5], off offset:256
	s_and_saveexec_b64 s[0:1], vcc
	s_cbranch_execz .LBB0_1654
	s_waitcnt lgkmcnt(0)
	v_add_f32_e32 v0, v0, v1
	ds_write_b32 v114, v0 offset:2816
